# LayerNorm phases: the sample row of waves 0-1 (with its split-K partial rows) is loaded ahead of the first prompt row and normalised while that row is in flight, instead of as an exposed tail
# speedup vs baseline: 1.0030x; 1.0030x over previous
; __device__ __forceinline__ int otid() { int t = threadIdx.x; asm volatile("" : "+v"(t)); return t; }
; __device__ __forceinline__ void phase_ln(float* R, const float* __restrict__ g, const float* __restrict__ b, bf16_t* xbf, float samp_scale, const float* __restrict__ part, int nsplit, bool f32_all) {
;   const int tid = otid(), lane = tid & 63, gw = blockIdx.x * 8 + (tid >> 6), nw = gridDim.x * 8;
;   f32x4 gv[4], bv[4];
; #pragma unroll
;   for (int i = 0; i < 4; ++i) { gv[i] = *(const f32x4*)(g + i * 256 + lane * 4); bv[i] = *(const f32x4*)(b + i * 256 + lane * 4); }
;   for (int r = gw; r < MT; r += nw) {
;     float* row = R + (size_t)r * 1024;
;     f32x4 v[4];
; #pragma unroll
;     for (int i = 0; i < 4; ++i) v[i] = *(const f32x4*)(row + i * 256 + lane * 4);
;     if (r >= MP) {
;       for (int sp = 0; sp < nsplit; ++sp) {
;         const float* prow = part + ((size_t)sp * MS + (r - MP)) * 1024;
; #pragma unroll
;         for (int i = 0; i < 4; ++i) v[i] = v[i] + *(const f32x4*)(prow + i * 256 + lane * 4);
;       }
;     }
;     float s = 0.f;
; #pragma unroll
;     for (int i = 0; i < 4; ++i) s += v[i][0] + v[i][1] + v[i][2] + v[i][3];
; #pragma unroll
;     for (int o = 32; o >= 1; o >>= 1) s += __shfl_xor(s, o);
;     const float mean = s * (1.f / 1024.f);
;     float ss = 0.f;
; #pragma unroll
;     for (int i = 0; i < 4; ++i) { v[i] = v[i] - mean; ss += v[i][0] * v[i][0] + v[i][1] * v[i][1] + v[i][2] * v[i][2] + v[i][3] * v[i][3]; }
; #pragma unroll
;     for (int o = 32; o >= 1; o >>= 1) ss += __shfl_xor(ss, o);
;     const float rstd = rsqrtf(ss * (1.f / 1024.f) + LN_EPS);
.LBB0_3720:
	s_or_b64 exec, exec, s[0:1]
	v_readlane_b32 s0, v254, 51
	s_nop 0
	s_cmp_lg_u32 s0, 0
	s_cbranch_scc1 .Lln1_orig
	v_readlane_b32 s6, v254, 2
	v_readlane_b32 s7, v254, 3
	v_readlane_b32 s8, v255, 22
	s_waitcnt lgkmcnt(0)
	s_barrier
	s_load_dwordx4 s[0:3], s[6:7], 0x78
	s_load_dwordx4 s[4:7], s[6:7], 0xa8
	v_readlane_b32 s9, v254, 15
	v_readfirstlane_b32 s10, v244
	v_lshlrev_b32_e32 v114, 4, v252
	v_lshlrev_b32_e32 v115, 3, v252
	s_lshr_b32 s10, s10, 6
	s_add_i32 s9, s9, s10
	s_lshl_b32 s11, s8, 12
	s_waitcnt lgkmcnt(0)
	s_add_u32 s0, s0, s11
	s_addc_u32 s1, s1, 0
	s_add_u32 s2, s2, s11
	s_addc_u32 s3, s3, 0
	global_load_dwordx4 v[34:37], v114, s[0:1] offset:0
	global_load_dwordx4 v[38:41], v114, s[0:1] offset:1024
	global_load_dwordx4 v[42:45], v114, s[0:1] offset:2048
	global_load_dwordx4 v[46:49], v114, s[0:1] offset:3072
	global_load_dwordx4 v[50:53], v114, s[2:3] offset:0
	global_load_dwordx4 v[54:57], v114, s[2:3] offset:1024
	global_load_dwordx4 v[58:61], v114, s[2:3] offset:2048
	global_load_dwordx4 v[62:65], v114, s[2:3] offset:3072
	s_lshl_b32 s11, s9, 12
	s_add_u32 s0, s4, s11
	s_addc_u32 s1, s5, 0
	s_lshl_b32 s11, s9, 11
	s_add_u32 s11, s11, 0x39c0000
	s_add_u32 s2, s6, s11
	s_addc_u32 s3, s7, 0
	s_cmp_ge_u32 s10, 2
	s_cbranch_scc1 .Lln1_nosa
	v_readlane_b32 s9, v254, 6
	s_nop 0
	s_lshl_b32 s9, s9, 1
	s_add_i32 s9, s9, s10
	s_lshl_b32 s11, s9, 12
	s_add_u32 s11, s11, 0x1e482000
	s_add_u32 s10, s6, s11
	s_addc_u32 s11, s7, 0
	s_lshl_b32 vcc_lo, s9, 12
	s_add_u32 vcc_lo, vcc_lo, 0x8000000
	s_add_u32 s4, s4, vcc_lo
	s_addc_u32 s5, s5, 0
	s_lshl_b32 vcc_lo, s9, 11
	s_add_u32 vcc_lo, vcc_lo, 0x79c0000
	s_add_u32 s6, s6, vcc_lo
	s_addc_u32 s7, s7, 0
	global_load_dwordx4 v[202:205], v114, s[4:5] offset:0
	global_load_dwordx4 v[206:209], v114, s[4:5] offset:1024
	global_load_dwordx4 v[210:213], v114, s[4:5] offset:2048
	global_load_dwordx4 v[214:217], v114, s[4:5] offset:3072
	global_load_dwordx4 v[122:125], v114, s[10:11] offset:0
	global_load_dwordx4 v[126:129], v114, s[10:11] offset:1024
	global_load_dwordx4 v[130:133], v114, s[10:11] offset:2048
	global_load_dwordx4 v[134:137], v114, s[10:11] offset:3072
	s_add_u32 s10, s10, 0x200000
	s_addc_u32 s11, s11, 0
	global_load_dwordx4 v[138:141], v114, s[10:11] offset:0
	global_load_dwordx4 v[142:145], v114, s[10:11] offset:1024
	global_load_dwordx4 v[146:149], v114, s[10:11] offset:2048
	global_load_dwordx4 v[150:153], v114, s[10:11] offset:3072
	s_add_u32 s10, s10, 0x200000
	s_addc_u32 s11, s11, 0
	global_load_dwordx4 v[154:157], v114, s[10:11] offset:0
	global_load_dwordx4 v[158:161], v114, s[10:11] offset:1024
	global_load_dwordx4 v[162:165], v114, s[10:11] offset:2048
	global_load_dwordx4 v[166:169], v114, s[10:11] offset:3072
	s_add_u32 s10, s10, 0x200000
	s_addc_u32 s11, s11, 0
	global_load_dwordx4 v[170:173], v114, s[10:11] offset:0
	global_load_dwordx4 v[174:177], v114, s[10:11] offset:1024
	global_load_dwordx4 v[178:181], v114, s[10:11] offset:2048
	global_load_dwordx4 v[182:185], v114, s[10:11] offset:3072
.Lln1_nosa:
	global_load_dwordx4 v[0:3], v114, s[0:1] offset:0
	global_load_dwordx4 v[4:7], v114, s[0:1] offset:1024
	global_load_dwordx4 v[8:11], v114, s[0:1] offset:2048
	global_load_dwordx4 v[12:15], v114, s[0:1] offset:3072
	v_readfirstlane_b32 s10, v244
	s_lshr_b32 s10, s10, 6
	s_cmp_ge_u32 s10, 2
	s_cbranch_scc1 .Lln1_nosb
	s_waitcnt vmcnt(4)
	v_pk_add_f32 v[202:203], v[202:203], v[122:123]
	v_pk_add_f32 v[204:205], v[204:205], v[124:125]
	v_pk_add_f32 v[206:207], v[206:207], v[126:127]
	v_pk_add_f32 v[208:209], v[208:209], v[128:129]
	v_pk_add_f32 v[210:211], v[210:211], v[130:131]
	v_pk_add_f32 v[212:213], v[212:213], v[132:133]
	v_pk_add_f32 v[214:215], v[214:215], v[134:135]
	v_pk_add_f32 v[216:217], v[216:217], v[136:137]
	v_pk_add_f32 v[202:203], v[202:203], v[138:139]
	v_pk_add_f32 v[204:205], v[204:205], v[140:141]
	v_pk_add_f32 v[206:207], v[206:207], v[142:143]
	v_pk_add_f32 v[208:209], v[208:209], v[144:145]
	v_pk_add_f32 v[210:211], v[210:211], v[146:147]
	v_pk_add_f32 v[212:213], v[212:213], v[148:149]
	v_pk_add_f32 v[214:215], v[214:215], v[150:151]
	v_pk_add_f32 v[216:217], v[216:217], v[152:153]
	v_pk_add_f32 v[202:203], v[202:203], v[154:155]
	v_pk_add_f32 v[204:205], v[204:205], v[156:157]
	v_pk_add_f32 v[206:207], v[206:207], v[158:159]
	v_pk_add_f32 v[208:209], v[208:209], v[160:161]
	v_pk_add_f32 v[210:211], v[210:211], v[162:163]
	v_pk_add_f32 v[212:213], v[212:213], v[164:165]
	v_pk_add_f32 v[214:215], v[214:215], v[166:167]
	v_pk_add_f32 v[216:217], v[216:217], v[168:169]
	v_pk_add_f32 v[202:203], v[202:203], v[170:171]
	v_pk_add_f32 v[204:205], v[204:205], v[172:173]
	v_pk_add_f32 v[206:207], v[206:207], v[174:175]
	v_pk_add_f32 v[208:209], v[208:209], v[176:177]
	v_pk_add_f32 v[210:211], v[210:211], v[178:179]
	v_pk_add_f32 v[212:213], v[212:213], v[180:181]
	v_pk_add_f32 v[214:215], v[214:215], v[182:183]
	v_pk_add_f32 v[216:217], v[216:217], v[184:185]
	v_pk_add_f32 v[66:67], v[202:203], v[204:205]
	v_pk_add_f32 v[68:69], v[206:207], v[208:209]
	v_pk_add_f32 v[70:71], v[210:211], v[212:213]
	v_pk_add_f32 v[72:73], v[214:215], v[216:217]
	v_pk_add_f32 v[66:67], v[66:67], v[68:69]
	v_pk_add_f32 v[70:71], v[70:71], v[72:73]
	v_pk_add_f32 v[66:67], v[66:67], v[70:71]
	v_add_f32_e32 v66, v66, v67
	s_nop 1
	v_add_f32_dpp v66, v66, v66 row_shr:1 row_mask:0xf bank_mask:0xf bound_ctrl:1
	s_nop 1
	v_add_f32_dpp v66, v66, v66 row_shr:2 row_mask:0xf bank_mask:0xf bound_ctrl:1
	s_nop 1
	v_add_f32_dpp v66, v66, v66 row_shr:4 row_mask:0xf bank_mask:0xf bound_ctrl:1
	s_nop 1
	v_add_f32_dpp v66, v66, v66 row_shr:8 row_mask:0xf bank_mask:0xf bound_ctrl:1
; __device__ __forceinline__ void phase_ln(float* R, const float* __restrict__ g, const float* __restrict__ b, bf16_t* xbf, float samp_scale, const float* __restrict__ part, int nsplit, bool f32_all) {
;     ...
;     const float mean = s * (1.f / 1024.f);
;     float ss = 0.f;
; #pragma unroll
;     for (int i = 0; i < 4; ++i) { v[i] = v[i] - mean; ss += v[i][0] * v[i][0] + v[i][1] * v[i][1] + v[i][2] * v[i][2] + v[i][3] * v[i][3]; }
; #pragma unroll
;     for (int o = 32; o >= 1; o >>= 1) ss += __shfl_xor(ss, o);
;     const float rstd = rsqrtf(ss * (1.f / 1024.f) + LN_EPS);
; #pragma unroll
;     for (int i = 0; i < 4; ++i) {
;       const f32x4 y = v[i] * rstd * gv[i] + bv[i];
;       if (r >= MP) *(f32x4*)(row + i * 256 + lane * 4) = y * samp_scale;
;       else if (f32_all) *(f32x4*)(row + i * 256 + lane * 4) = y;
;       if (xbf) {
;         u32x2 wv;
;         wv[0] = cvt_pk_bf16(y[0], y[1]); wv[1] = cvt_pk_bf16(y[2], y[3]);
;         *(u32x2*)(xbf + (size_t)r * 1024 + i * 256 + lane * 4) = wv;
;       }
;     }
	s_nop 0
	v_readlane_b32 s9, v66, 15
	v_readlane_b32 s10, v66, 31
	v_readlane_b32 s11, v66, 47
	v_readlane_b32 vcc_lo, v66, 63
	s_nop 1
	v_mov_b32_e32 v66, s9
	v_add_f32_e32 v66, s10, v66
	v_add_f32_e32 v66, s11, v66
	v_add_f32_e32 v66, vcc_lo, v66
	v_mul_f32_e32 v116, 0x3a800000, v66
	v_mov_b32_e32 v117, v116
	v_pk_add_f32 v[202:203], v[202:203], v[116:117] neg_lo:[0,1] neg_hi:[0,1]
	v_pk_add_f32 v[204:205], v[204:205], v[116:117] neg_lo:[0,1] neg_hi:[0,1]
	v_pk_add_f32 v[206:207], v[206:207], v[116:117] neg_lo:[0,1] neg_hi:[0,1]
	v_pk_add_f32 v[208:209], v[208:209], v[116:117] neg_lo:[0,1] neg_hi:[0,1]
	v_pk_add_f32 v[210:211], v[210:211], v[116:117] neg_lo:[0,1] neg_hi:[0,1]
	v_pk_add_f32 v[212:213], v[212:213], v[116:117] neg_lo:[0,1] neg_hi:[0,1]
	v_pk_add_f32 v[214:215], v[214:215], v[116:117] neg_lo:[0,1] neg_hi:[0,1]
	v_pk_add_f32 v[216:217], v[216:217], v[116:117] neg_lo:[0,1] neg_hi:[0,1]
	v_pk_mul_f32 v[66:67], v[202:203], v[202:203]
	v_pk_mul_f32 v[68:69], v[204:205], v[204:205]
	v_pk_fma_f32 v[66:67], v[206:207], v[206:207], v[66:67]
	v_pk_fma_f32 v[68:69], v[208:209], v[208:209], v[68:69]
	v_pk_fma_f32 v[66:67], v[210:211], v[210:211], v[66:67]
	v_pk_fma_f32 v[68:69], v[212:213], v[212:213], v[68:69]
	v_pk_fma_f32 v[66:67], v[214:215], v[214:215], v[66:67]
	v_pk_fma_f32 v[68:69], v[216:217], v[216:217], v[68:69]
	v_pk_add_f32 v[66:67], v[66:67], v[68:69]
	v_add_f32_e32 v66, v66, v67
	s_nop 1
	v_add_f32_dpp v66, v66, v66 row_shr:1 row_mask:0xf bank_mask:0xf bound_ctrl:1
	s_nop 1
	v_add_f32_dpp v66, v66, v66 row_shr:2 row_mask:0xf bank_mask:0xf bound_ctrl:1
	s_nop 1
	v_add_f32_dpp v66, v66, v66 row_shr:4 row_mask:0xf bank_mask:0xf bound_ctrl:1
	s_nop 1
	v_add_f32_dpp v66, v66, v66 row_shr:8 row_mask:0xf bank_mask:0xf bound_ctrl:1
	s_nop 0
	v_readlane_b32 s9, v66, 15
	v_readlane_b32 s10, v66, 31
	v_readlane_b32 s11, v66, 47
	v_readlane_b32 vcc_lo, v66, 63
	s_nop 1
	v_mov_b32_e32 v66, s9
	v_add_f32_e32 v66, s10, v66
	v_add_f32_e32 v66, s11, v66
	v_add_f32_e32 v66, vcc_lo, v66
	v_mul_f32_e32 v66, 0x3a800000, v66
	v_add_f32_e32 v66, 0x3727c5ac, v66
	v_rsq_f32_e32 v118, v66
	s_nop 0
	v_mov_b32_e32 v119, v118
	v_pk_mul_f32 v[202:203], v[202:203], v[118:119]
	v_pk_mul_f32 v[204:205], v[204:205], v[118:119]
	v_pk_mul_f32 v[206:207], v[206:207], v[118:119]
	v_pk_mul_f32 v[208:209], v[208:209], v[118:119]
	v_pk_mul_f32 v[210:211], v[210:211], v[118:119]
	v_pk_mul_f32 v[212:213], v[212:213], v[118:119]
	v_pk_mul_f32 v[214:215], v[214:215], v[118:119]
	v_pk_mul_f32 v[216:217], v[216:217], v[118:119]
	v_pk_fma_f32 v[76:77], v[202:203], v[34:35], v[50:51]
	v_pk_fma_f32 v[78:79], v[204:205], v[36:37], v[52:53]
	v_pk_fma_f32 v[80:81], v[206:207], v[38:39], v[54:55]
	v_pk_fma_f32 v[82:83], v[208:209], v[40:41], v[56:57]
	v_pk_fma_f32 v[84:85], v[210:211], v[42:43], v[58:59]
	v_pk_fma_f32 v[86:87], v[212:213], v[44:45], v[60:61]
	v_pk_fma_f32 v[88:89], v[214:215], v[46:47], v[62:63]
	v_pk_fma_f32 v[90:91], v[216:217], v[48:49], v[64:65]
	s_mov_b32 s9, 0x3fb504f3
	v_mov_b32_e32 v120, s9
	v_mov_b32_e32 v121, s9
	v_pk_mul_f32 v[202:203], v[76:77], v[120:121]
	v_pk_mul_f32 v[204:205], v[78:79], v[120:121]
	v_pk_mul_f32 v[206:207], v[80:81], v[120:121]
	v_pk_mul_f32 v[208:209], v[82:83], v[120:121]
	v_pk_mul_f32 v[210:211], v[84:85], v[120:121]
	v_pk_mul_f32 v[212:213], v[86:87], v[120:121]
	v_pk_mul_f32 v[214:215], v[88:89], v[120:121]
	v_pk_mul_f32 v[216:217], v[90:91], v[120:121]
	global_store_dwordx4 v114, v[202:205], s[4:5] offset:0
	global_store_dwordx4 v114, v[206:209], s[4:5] offset:1024
	global_store_dwordx4 v114, v[210:213], s[4:5] offset:2048
	global_store_dwordx4 v114, v[214:217], s[4:5] offset:3072
	v_cvt_pk_bf16_f32 v92, v76, v77
	v_cvt_pk_bf16_f32 v93, v78, v79
	v_cvt_pk_bf16_f32 v94, v80, v81
	v_cvt_pk_bf16_f32 v95, v82, v83
	v_cvt_pk_bf16_f32 v96, v84, v85
	v_cvt_pk_bf16_f32 v97, v86, v87
	v_cvt_pk_bf16_f32 v98, v88, v89
	v_cvt_pk_bf16_f32 v99, v90, v91
	global_store_dwordx2 v115, v[92:93], s[6:7] offset:0
	global_store_dwordx2 v115, v[94:95], s[6:7] offset:512
	global_store_dwordx2 v115, v[96:97], s[6:7] offset:1024
	global_store_dwordx2 v115, v[98:99], s[6:7] offset:1536
.Lln1_nosb:
	s_add_u32 s0, s0, 0x800000
	s_addc_u32 s1, s1, 0
	global_load_dwordx4 v[18:21], v114, s[0:1] offset:0
	global_load_dwordx4 v[22:25], v114, s[0:1] offset:1024
	global_load_dwordx4 v[26:29], v114, s[0:1] offset:2048
	global_load_dwordx4 v[30:33], v114, s[0:1] offset:3072
	s_waitcnt vmcnt(4)
; __device__ __forceinline__ void phase_ln(float* R, const float* __restrict__ g, const float* __restrict__ b, bf16_t* xbf, float samp_scale, const float* __restrict__ part, int nsplit, bool f32_all) {
;     ...
;     float s = 0.f;
; #pragma unroll
;     for (int i = 0; i < 4; ++i) s += v[i][0] + v[i][1] + v[i][2] + v[i][3];
; #pragma unroll
;     for (int o = 32; o >= 1; o >>= 1) s += __shfl_xor(s, o);
;     const float mean = s * (1.f / 1024.f);
;     float ss = 0.f;
; #pragma unroll
;     for (int i = 0; i < 4; ++i) { v[i] = v[i] - mean; ss += v[i][0] * v[i][0] + v[i][1] * v[i][1] + v[i][2] * v[i][2] + v[i][3] * v[i][3]; }
; #pragma unroll
;     for (int o = 32; o >= 1; o >>= 1) ss += __shfl_xor(ss, o);
;     const float rstd = rsqrtf(ss * (1.f / 1024.f) + LN_EPS);
; #pragma unroll
;     for (int i = 0; i < 4; ++i) {
;       const f32x4 y = v[i] * rstd * gv[i] + bv[i];
;       if (r >= MP) *(f32x4*)(row + i * 256 + lane * 4) = y * samp_scale;
;       else if (f32_all) *(f32x4*)(row + i * 256 + lane * 4) = y;
;       if (xbf) {
;         u32x2 wv;
;         wv[0] = cvt_pk_bf16(y[0], y[1]); wv[1] = cvt_pk_bf16(y[2], y[3]);
;         *(u32x2*)(xbf + (size_t)r * 1024 + i * 256 + lane * 4) = wv;
;       }
;     }
	v_pk_add_f32 v[66:67], v[0:1], v[2:3]
	v_pk_add_f32 v[68:69], v[4:5], v[6:7]
	v_pk_add_f32 v[70:71], v[8:9], v[10:11]
	v_pk_add_f32 v[72:73], v[12:13], v[14:15]
	v_pk_add_f32 v[66:67], v[66:67], v[68:69]
	v_pk_add_f32 v[70:71], v[70:71], v[72:73]
	v_pk_add_f32 v[66:67], v[66:67], v[70:71]
	v_add_f32_e32 v66, v66, v67
	s_nop 1
	v_add_f32_dpp v66, v66, v66 row_shr:1 row_mask:0xf bank_mask:0xf bound_ctrl:1
	s_nop 1
	v_add_f32_dpp v66, v66, v66 row_shr:2 row_mask:0xf bank_mask:0xf bound_ctrl:1
	s_nop 1
	v_add_f32_dpp v66, v66, v66 row_shr:4 row_mask:0xf bank_mask:0xf bound_ctrl:1
	s_nop 1
	v_add_f32_dpp v66, v66, v66 row_shr:8 row_mask:0xf bank_mask:0xf bound_ctrl:1
	s_nop 0
	v_readlane_b32 s9, v66, 15
	v_readlane_b32 s10, v66, 31
	v_readlane_b32 s11, v66, 47
	v_readlane_b32 vcc_lo, v66, 63
	s_nop 1
	v_mov_b32_e32 v66, s9
	v_add_f32_e32 v66, s10, v66
	v_add_f32_e32 v66, s11, v66
	v_add_f32_e32 v66, vcc_lo, v66
	v_mul_f32_e32 v116, 0x3a800000, v66
	v_mov_b32_e32 v117, v116
	v_pk_add_f32 v[0:1], v[0:1], v[116:117] neg_lo:[0,1] neg_hi:[0,1]
	v_pk_add_f32 v[2:3], v[2:3], v[116:117] neg_lo:[0,1] neg_hi:[0,1]
	v_pk_add_f32 v[4:5], v[4:5], v[116:117] neg_lo:[0,1] neg_hi:[0,1]
	v_pk_add_f32 v[6:7], v[6:7], v[116:117] neg_lo:[0,1] neg_hi:[0,1]
	v_pk_add_f32 v[8:9], v[8:9], v[116:117] neg_lo:[0,1] neg_hi:[0,1]
	v_pk_add_f32 v[10:11], v[10:11], v[116:117] neg_lo:[0,1] neg_hi:[0,1]
	v_pk_add_f32 v[12:13], v[12:13], v[116:117] neg_lo:[0,1] neg_hi:[0,1]
	v_pk_add_f32 v[14:15], v[14:15], v[116:117] neg_lo:[0,1] neg_hi:[0,1]
	v_pk_mul_f32 v[66:67], v[0:1], v[0:1]
	v_pk_mul_f32 v[68:69], v[2:3], v[2:3]
	v_pk_fma_f32 v[66:67], v[4:5], v[4:5], v[66:67]
	v_pk_fma_f32 v[68:69], v[6:7], v[6:7], v[68:69]
	v_pk_fma_f32 v[66:67], v[8:9], v[8:9], v[66:67]
	v_pk_fma_f32 v[68:69], v[10:11], v[10:11], v[68:69]
	v_pk_fma_f32 v[66:67], v[12:13], v[12:13], v[66:67]
	v_pk_fma_f32 v[68:69], v[14:15], v[14:15], v[68:69]
	v_pk_add_f32 v[66:67], v[66:67], v[68:69]
	v_add_f32_e32 v66, v66, v67
	s_nop 1
	v_add_f32_dpp v66, v66, v66 row_shr:1 row_mask:0xf bank_mask:0xf bound_ctrl:1
	s_nop 1
	v_add_f32_dpp v66, v66, v66 row_shr:2 row_mask:0xf bank_mask:0xf bound_ctrl:1
	s_nop 1
	v_add_f32_dpp v66, v66, v66 row_shr:4 row_mask:0xf bank_mask:0xf bound_ctrl:1
	s_nop 1
	v_add_f32_dpp v66, v66, v66 row_shr:8 row_mask:0xf bank_mask:0xf bound_ctrl:1
	s_nop 0
	v_readlane_b32 s9, v66, 15
	v_readlane_b32 s10, v66, 31
	v_readlane_b32 s11, v66, 47
	v_readlane_b32 vcc_lo, v66, 63
	s_nop 1
	v_mov_b32_e32 v66, s9
	v_add_f32_e32 v66, s10, v66
	v_add_f32_e32 v66, s11, v66
	v_add_f32_e32 v66, vcc_lo, v66
	v_mul_f32_e32 v66, 0x3a800000, v66
	v_add_f32_e32 v66, 0x3727c5ac, v66
	v_rsq_f32_e32 v118, v66
	s_nop 0
	v_mov_b32_e32 v119, v118
	v_pk_mul_f32 v[0:1], v[0:1], v[118:119]
	v_pk_mul_f32 v[2:3], v[2:3], v[118:119]
	v_pk_mul_f32 v[4:5], v[4:5], v[118:119]
	v_pk_mul_f32 v[6:7], v[6:7], v[118:119]
	v_pk_mul_f32 v[8:9], v[8:9], v[118:119]
	v_pk_mul_f32 v[10:11], v[10:11], v[118:119]
	v_pk_mul_f32 v[12:13], v[12:13], v[118:119]
	v_pk_mul_f32 v[14:15], v[14:15], v[118:119]
	v_pk_fma_f32 v[76:77], v[0:1], v[34:35], v[50:51]
	v_pk_fma_f32 v[78:79], v[2:3], v[36:37], v[52:53]
	v_pk_fma_f32 v[80:81], v[4:5], v[38:39], v[54:55]
	v_pk_fma_f32 v[82:83], v[6:7], v[40:41], v[56:57]
	v_pk_fma_f32 v[84:85], v[8:9], v[42:43], v[58:59]
	v_pk_fma_f32 v[86:87], v[10:11], v[44:45], v[60:61]
	v_pk_fma_f32 v[88:89], v[12:13], v[46:47], v[62:63]
	v_pk_fma_f32 v[90:91], v[14:15], v[48:49], v[64:65]
	v_cvt_pk_bf16_f32 v92, v76, v77
	v_cvt_pk_bf16_f32 v93, v78, v79
	v_cvt_pk_bf16_f32 v94, v80, v81
	v_cvt_pk_bf16_f32 v95, v82, v83
	v_cvt_pk_bf16_f32 v96, v84, v85
	v_cvt_pk_bf16_f32 v97, v86, v87
	v_cvt_pk_bf16_f32 v98, v88, v89
	v_cvt_pk_bf16_f32 v99, v90, v91
	global_store_dwordx2 v115, v[92:93], s[2:3] offset:0
	global_store_dwordx2 v115, v[94:95], s[2:3] offset:512
	global_store_dwordx2 v115, v[96:97], s[2:3] offset:1024
	global_store_dwordx2 v115, v[98:99], s[2:3] offset:1536
	s_add_u32 s2, s2, 0x400000
	s_addc_u32 s3, s3, 0
	s_add_u32 s0, s0, 0x800000
	s_addc_u32 s1, s1, 0
	global_load_dwordx4 v[0:3], v114, s[0:1] offset:0
	global_load_dwordx4 v[4:7], v114, s[0:1] offset:1024
	global_load_dwordx4 v[8:11], v114, s[0:1] offset:2048
	global_load_dwordx4 v[12:15], v114, s[0:1] offset:3072
	s_waitcnt vmcnt(8)
; __device__ __forceinline__ void phase_ln(float* R, const float* __restrict__ g, const float* __restrict__ b, bf16_t* xbf, float samp_scale, const float* __restrict__ part, int nsplit, bool f32_all) {
;     ...
;     float s = 0.f;
; #pragma unroll
;     for (int i = 0; i < 4; ++i) s += v[i][0] + v[i][1] + v[i][2] + v[i][3];
; #pragma unroll
;     for (int o = 32; o >= 1; o >>= 1) s += __shfl_xor(s, o);
;     const float mean = s * (1.f / 1024.f);
;     float ss = 0.f;
; #pragma unroll
;     for (int i = 0; i < 4; ++i) { v[i] = v[i] - mean; ss += v[i][0] * v[i][0] + v[i][1] * v[i][1] + v[i][2] * v[i][2] + v[i][3] * v[i][3]; }
; #pragma unroll
;     for (int o = 32; o >= 1; o >>= 1) ss += __shfl_xor(ss, o);
;     const float rstd = rsqrtf(ss * (1.f / 1024.f) + LN_EPS);
; #pragma unroll
;     for (int i = 0; i < 4; ++i) {
;       const f32x4 y = v[i] * rstd * gv[i] + bv[i];
;       if (r >= MP) *(f32x4*)(row + i * 256 + lane * 4) = y * samp_scale;
;       else if (f32_all) *(f32x4*)(row + i * 256 + lane * 4) = y;
;       if (xbf) {
;         u32x2 wv;
;         wv[0] = cvt_pk_bf16(y[0], y[1]); wv[1] = cvt_pk_bf16(y[2], y[3]);
;         *(u32x2*)(xbf + (size_t)r * 1024 + i * 256 + lane * 4) = wv;
;       }
;     }
	v_pk_add_f32 v[66:67], v[18:19], v[20:21]
	v_pk_add_f32 v[68:69], v[22:23], v[24:25]
	v_pk_add_f32 v[70:71], v[26:27], v[28:29]
	v_pk_add_f32 v[72:73], v[30:31], v[32:33]
	v_pk_add_f32 v[66:67], v[66:67], v[68:69]
	v_pk_add_f32 v[70:71], v[70:71], v[72:73]
	v_pk_add_f32 v[66:67], v[66:67], v[70:71]
	v_add_f32_e32 v66, v66, v67
	s_nop 1
	v_add_f32_dpp v66, v66, v66 row_shr:1 row_mask:0xf bank_mask:0xf bound_ctrl:1
	s_nop 1
	v_add_f32_dpp v66, v66, v66 row_shr:2 row_mask:0xf bank_mask:0xf bound_ctrl:1
	s_nop 1
	v_add_f32_dpp v66, v66, v66 row_shr:4 row_mask:0xf bank_mask:0xf bound_ctrl:1
	s_nop 1
	v_add_f32_dpp v66, v66, v66 row_shr:8 row_mask:0xf bank_mask:0xf bound_ctrl:1
	s_nop 0
	v_readlane_b32 s9, v66, 15
	v_readlane_b32 s10, v66, 31
	v_readlane_b32 s11, v66, 47
	v_readlane_b32 vcc_lo, v66, 63
	s_nop 1
	v_mov_b32_e32 v66, s9
	v_add_f32_e32 v66, s10, v66
	v_add_f32_e32 v66, s11, v66
	v_add_f32_e32 v66, vcc_lo, v66
	v_mul_f32_e32 v116, 0x3a800000, v66
	v_mov_b32_e32 v117, v116
	v_pk_add_f32 v[18:19], v[18:19], v[116:117] neg_lo:[0,1] neg_hi:[0,1]
	v_pk_add_f32 v[20:21], v[20:21], v[116:117] neg_lo:[0,1] neg_hi:[0,1]
	v_pk_add_f32 v[22:23], v[22:23], v[116:117] neg_lo:[0,1] neg_hi:[0,1]
	v_pk_add_f32 v[24:25], v[24:25], v[116:117] neg_lo:[0,1] neg_hi:[0,1]
	v_pk_add_f32 v[26:27], v[26:27], v[116:117] neg_lo:[0,1] neg_hi:[0,1]
	v_pk_add_f32 v[28:29], v[28:29], v[116:117] neg_lo:[0,1] neg_hi:[0,1]
	v_pk_add_f32 v[30:31], v[30:31], v[116:117] neg_lo:[0,1] neg_hi:[0,1]
	v_pk_add_f32 v[32:33], v[32:33], v[116:117] neg_lo:[0,1] neg_hi:[0,1]
	v_pk_mul_f32 v[66:67], v[18:19], v[18:19]
	v_pk_mul_f32 v[68:69], v[20:21], v[20:21]
	v_pk_fma_f32 v[66:67], v[22:23], v[22:23], v[66:67]
	v_pk_fma_f32 v[68:69], v[24:25], v[24:25], v[68:69]
	v_pk_fma_f32 v[66:67], v[26:27], v[26:27], v[66:67]
	v_pk_fma_f32 v[68:69], v[28:29], v[28:29], v[68:69]
	v_pk_fma_f32 v[66:67], v[30:31], v[30:31], v[66:67]
	v_pk_fma_f32 v[68:69], v[32:33], v[32:33], v[68:69]
	v_pk_add_f32 v[66:67], v[66:67], v[68:69]
	v_add_f32_e32 v66, v66, v67
	s_nop 1
	v_add_f32_dpp v66, v66, v66 row_shr:1 row_mask:0xf bank_mask:0xf bound_ctrl:1
	s_nop 1
	v_add_f32_dpp v66, v66, v66 row_shr:2 row_mask:0xf bank_mask:0xf bound_ctrl:1
	s_nop 1
	v_add_f32_dpp v66, v66, v66 row_shr:4 row_mask:0xf bank_mask:0xf bound_ctrl:1
	s_nop 1
	v_add_f32_dpp v66, v66, v66 row_shr:8 row_mask:0xf bank_mask:0xf bound_ctrl:1
	s_nop 0
	v_readlane_b32 s9, v66, 15
	v_readlane_b32 s10, v66, 31
	v_readlane_b32 s11, v66, 47
	v_readlane_b32 vcc_lo, v66, 63
	s_nop 1
	v_mov_b32_e32 v66, s9
	v_add_f32_e32 v66, s10, v66
	v_add_f32_e32 v66, s11, v66
	v_add_f32_e32 v66, vcc_lo, v66
	v_mul_f32_e32 v66, 0x3a800000, v66
	v_add_f32_e32 v66, 0x3727c5ac, v66
	v_rsq_f32_e32 v118, v66
	s_nop 0
	v_mov_b32_e32 v119, v118
	v_pk_mul_f32 v[18:19], v[18:19], v[118:119]
	v_pk_mul_f32 v[20:21], v[20:21], v[118:119]
	v_pk_mul_f32 v[22:23], v[22:23], v[118:119]
	v_pk_mul_f32 v[24:25], v[24:25], v[118:119]
	v_pk_mul_f32 v[26:27], v[26:27], v[118:119]
	v_pk_mul_f32 v[28:29], v[28:29], v[118:119]
	v_pk_mul_f32 v[30:31], v[30:31], v[118:119]
	v_pk_mul_f32 v[32:33], v[32:33], v[118:119]
	v_pk_fma_f32 v[76:77], v[18:19], v[34:35], v[50:51]
	v_pk_fma_f32 v[78:79], v[20:21], v[36:37], v[52:53]
	v_pk_fma_f32 v[80:81], v[22:23], v[38:39], v[54:55]
	v_pk_fma_f32 v[82:83], v[24:25], v[40:41], v[56:57]
	v_pk_fma_f32 v[84:85], v[26:27], v[42:43], v[58:59]
	v_pk_fma_f32 v[86:87], v[28:29], v[44:45], v[60:61]
	v_pk_fma_f32 v[88:89], v[30:31], v[46:47], v[62:63]
	v_pk_fma_f32 v[90:91], v[32:33], v[48:49], v[64:65]
	v_cvt_pk_bf16_f32 v92, v76, v77
	v_cvt_pk_bf16_f32 v93, v78, v79
	v_cvt_pk_bf16_f32 v94, v80, v81
	v_cvt_pk_bf16_f32 v95, v82, v83
	v_cvt_pk_bf16_f32 v96, v84, v85
	v_cvt_pk_bf16_f32 v97, v86, v87
	v_cvt_pk_bf16_f32 v98, v88, v89
	v_cvt_pk_bf16_f32 v99, v90, v91
	global_store_dwordx2 v115, v[92:93], s[2:3] offset:0
	global_store_dwordx2 v115, v[94:95], s[2:3] offset:512
	global_store_dwordx2 v115, v[96:97], s[2:3] offset:1024
	global_store_dwordx2 v115, v[98:99], s[2:3] offset:1536
	s_add_u32 s2, s2, 0x400000
	s_addc_u32 s3, s3, 0
	s_add_u32 s0, s0, 0x800000
	s_addc_u32 s1, s1, 0
	global_load_dwordx4 v[18:21], v114, s[0:1] offset:0
	global_load_dwordx4 v[22:25], v114, s[0:1] offset:1024
	global_load_dwordx4 v[26:29], v114, s[0:1] offset:2048
	global_load_dwordx4 v[30:33], v114, s[0:1] offset:3072
	s_waitcnt vmcnt(8)
; __device__ __forceinline__ void phase_ln(float* R, const float* __restrict__ g, const float* __restrict__ b, bf16_t* xbf, float samp_scale, const float* __restrict__ part, int nsplit, bool f32_all) {
;     ...
;     float s = 0.f;
; #pragma unroll
;     for (int i = 0; i < 4; ++i) s += v[i][0] + v[i][1] + v[i][2] + v[i][3];
; #pragma unroll
;     for (int o = 32; o >= 1; o >>= 1) s += __shfl_xor(s, o);
;     const float mean = s * (1.f / 1024.f);
;     float ss = 0.f;
; #pragma unroll
;     for (int i = 0; i < 4; ++i) { v[i] = v[i] - mean; ss += v[i][0] * v[i][0] + v[i][1] * v[i][1] + v[i][2] * v[i][2] + v[i][3] * v[i][3]; }
; #pragma unroll
;     for (int o = 32; o >= 1; o >>= 1) ss += __shfl_xor(ss, o);
;     const float rstd = rsqrtf(ss * (1.f / 1024.f) + LN_EPS);
; #pragma unroll
;     for (int i = 0; i < 4; ++i) {
;       const f32x4 y = v[i] * rstd * gv[i] + bv[i];
;       if (r >= MP) *(f32x4*)(row + i * 256 + lane * 4) = y * samp_scale;
;       else if (f32_all) *(f32x4*)(row + i * 256 + lane * 4) = y;
;       if (xbf) {
;         u32x2 wv;
;         wv[0] = cvt_pk_bf16(y[0], y[1]); wv[1] = cvt_pk_bf16(y[2], y[3]);
;         *(u32x2*)(xbf + (size_t)r * 1024 + i * 256 + lane * 4) = wv;
;       }
;     }
	v_pk_add_f32 v[66:67], v[0:1], v[2:3]
	v_pk_add_f32 v[68:69], v[4:5], v[6:7]
	v_pk_add_f32 v[70:71], v[8:9], v[10:11]
	v_pk_add_f32 v[72:73], v[12:13], v[14:15]
	v_pk_add_f32 v[66:67], v[66:67], v[68:69]
	v_pk_add_f32 v[70:71], v[70:71], v[72:73]
	v_pk_add_f32 v[66:67], v[66:67], v[70:71]
	v_add_f32_e32 v66, v66, v67
	s_nop 1
	v_add_f32_dpp v66, v66, v66 row_shr:1 row_mask:0xf bank_mask:0xf bound_ctrl:1
	s_nop 1
	v_add_f32_dpp v66, v66, v66 row_shr:2 row_mask:0xf bank_mask:0xf bound_ctrl:1
	s_nop 1
	v_add_f32_dpp v66, v66, v66 row_shr:4 row_mask:0xf bank_mask:0xf bound_ctrl:1
	s_nop 1
	v_add_f32_dpp v66, v66, v66 row_shr:8 row_mask:0xf bank_mask:0xf bound_ctrl:1
	s_nop 0
	v_readlane_b32 s9, v66, 15
	v_readlane_b32 s10, v66, 31
	v_readlane_b32 s11, v66, 47
	v_readlane_b32 vcc_lo, v66, 63
	s_nop 1
	v_mov_b32_e32 v66, s9
	v_add_f32_e32 v66, s10, v66
	v_add_f32_e32 v66, s11, v66
	v_add_f32_e32 v66, vcc_lo, v66
	v_mul_f32_e32 v116, 0x3a800000, v66
	v_mov_b32_e32 v117, v116
	v_pk_add_f32 v[0:1], v[0:1], v[116:117] neg_lo:[0,1] neg_hi:[0,1]
	v_pk_add_f32 v[2:3], v[2:3], v[116:117] neg_lo:[0,1] neg_hi:[0,1]
	v_pk_add_f32 v[4:5], v[4:5], v[116:117] neg_lo:[0,1] neg_hi:[0,1]
	v_pk_add_f32 v[6:7], v[6:7], v[116:117] neg_lo:[0,1] neg_hi:[0,1]
	v_pk_add_f32 v[8:9], v[8:9], v[116:117] neg_lo:[0,1] neg_hi:[0,1]
	v_pk_add_f32 v[10:11], v[10:11], v[116:117] neg_lo:[0,1] neg_hi:[0,1]
	v_pk_add_f32 v[12:13], v[12:13], v[116:117] neg_lo:[0,1] neg_hi:[0,1]
	v_pk_add_f32 v[14:15], v[14:15], v[116:117] neg_lo:[0,1] neg_hi:[0,1]
	v_pk_mul_f32 v[66:67], v[0:1], v[0:1]
	v_pk_mul_f32 v[68:69], v[2:3], v[2:3]
	v_pk_fma_f32 v[66:67], v[4:5], v[4:5], v[66:67]
	v_pk_fma_f32 v[68:69], v[6:7], v[6:7], v[68:69]
	v_pk_fma_f32 v[66:67], v[8:9], v[8:9], v[66:67]
	v_pk_fma_f32 v[68:69], v[10:11], v[10:11], v[68:69]
	v_pk_fma_f32 v[66:67], v[12:13], v[12:13], v[66:67]
	v_pk_fma_f32 v[68:69], v[14:15], v[14:15], v[68:69]
	v_pk_add_f32 v[66:67], v[66:67], v[68:69]
	v_add_f32_e32 v66, v66, v67
	s_nop 1
	v_add_f32_dpp v66, v66, v66 row_shr:1 row_mask:0xf bank_mask:0xf bound_ctrl:1
	s_nop 1
	v_add_f32_dpp v66, v66, v66 row_shr:2 row_mask:0xf bank_mask:0xf bound_ctrl:1
	s_nop 1
	v_add_f32_dpp v66, v66, v66 row_shr:4 row_mask:0xf bank_mask:0xf bound_ctrl:1
	s_nop 1
	v_add_f32_dpp v66, v66, v66 row_shr:8 row_mask:0xf bank_mask:0xf bound_ctrl:1
	s_nop 0
	v_readlane_b32 s9, v66, 15
	v_readlane_b32 s10, v66, 31
	v_readlane_b32 s11, v66, 47
	v_readlane_b32 vcc_lo, v66, 63
	s_nop 1
	v_mov_b32_e32 v66, s9
	v_add_f32_e32 v66, s10, v66
	v_add_f32_e32 v66, s11, v66
	v_add_f32_e32 v66, vcc_lo, v66
	v_mul_f32_e32 v66, 0x3a800000, v66
	v_add_f32_e32 v66, 0x3727c5ac, v66
	v_rsq_f32_e32 v118, v66
	s_nop 0
	v_mov_b32_e32 v119, v118
	v_pk_mul_f32 v[0:1], v[0:1], v[118:119]
	v_pk_mul_f32 v[2:3], v[2:3], v[118:119]
	v_pk_mul_f32 v[4:5], v[4:5], v[118:119]
	v_pk_mul_f32 v[6:7], v[6:7], v[118:119]
	v_pk_mul_f32 v[8:9], v[8:9], v[118:119]
	v_pk_mul_f32 v[10:11], v[10:11], v[118:119]
	v_pk_mul_f32 v[12:13], v[12:13], v[118:119]
	v_pk_mul_f32 v[14:15], v[14:15], v[118:119]
	v_pk_fma_f32 v[76:77], v[0:1], v[34:35], v[50:51]
	v_pk_fma_f32 v[78:79], v[2:3], v[36:37], v[52:53]
	v_pk_fma_f32 v[80:81], v[4:5], v[38:39], v[54:55]
	v_pk_fma_f32 v[82:83], v[6:7], v[40:41], v[56:57]
	v_pk_fma_f32 v[84:85], v[8:9], v[42:43], v[58:59]
	v_pk_fma_f32 v[86:87], v[10:11], v[44:45], v[60:61]
	v_pk_fma_f32 v[88:89], v[12:13], v[46:47], v[62:63]
	v_pk_fma_f32 v[90:91], v[14:15], v[48:49], v[64:65]
	v_cvt_pk_bf16_f32 v92, v76, v77
	v_cvt_pk_bf16_f32 v93, v78, v79
	v_cvt_pk_bf16_f32 v94, v80, v81
	v_cvt_pk_bf16_f32 v95, v82, v83
	v_cvt_pk_bf16_f32 v96, v84, v85
	v_cvt_pk_bf16_f32 v97, v86, v87
	v_cvt_pk_bf16_f32 v98, v88, v89
	v_cvt_pk_bf16_f32 v99, v90, v91
	global_store_dwordx2 v115, v[92:93], s[2:3] offset:0
	global_store_dwordx2 v115, v[94:95], s[2:3] offset:512
	global_store_dwordx2 v115, v[96:97], s[2:3] offset:1024
	global_store_dwordx2 v115, v[98:99], s[2:3] offset:1536
	s_add_u32 s2, s2, 0x400000
	s_addc_u32 s3, s3, 0
	s_add_u32 s0, s0, 0x800000
	s_addc_u32 s1, s1, 0
	global_load_dwordx4 v[0:3], v114, s[0:1] offset:0
	global_load_dwordx4 v[4:7], v114, s[0:1] offset:1024
	global_load_dwordx4 v[8:11], v114, s[0:1] offset:2048
	global_load_dwordx4 v[12:15], v114, s[0:1] offset:3072
	s_waitcnt vmcnt(8)
; __device__ __forceinline__ void phase_ln(float* R, const float* __restrict__ g, const float* __restrict__ b, bf16_t* xbf, float samp_scale, const float* __restrict__ part, int nsplit, bool f32_all) {
;     ...
;     float s = 0.f;
; #pragma unroll
;     for (int i = 0; i < 4; ++i) s += v[i][0] + v[i][1] + v[i][2] + v[i][3];
; #pragma unroll
;     for (int o = 32; o >= 1; o >>= 1) s += __shfl_xor(s, o);
;     const float mean = s * (1.f / 1024.f);
;     float ss = 0.f;
; #pragma unroll
;     for (int i = 0; i < 4; ++i) { v[i] = v[i] - mean; ss += v[i][0] * v[i][0] + v[i][1] * v[i][1] + v[i][2] * v[i][2] + v[i][3] * v[i][3]; }
; #pragma unroll
;     for (int o = 32; o >= 1; o >>= 1) ss += __shfl_xor(ss, o);
;     const float rstd = rsqrtf(ss * (1.f / 1024.f) + LN_EPS);
; #pragma unroll
;     for (int i = 0; i < 4; ++i) {
;       const f32x4 y = v[i] * rstd * gv[i] + bv[i];
;       if (r >= MP) *(f32x4*)(row + i * 256 + lane * 4) = y * samp_scale;
;       else if (f32_all) *(f32x4*)(row + i * 256 + lane * 4) = y;
;       if (xbf) {
;         u32x2 wv;
;         wv[0] = cvt_pk_bf16(y[0], y[1]); wv[1] = cvt_pk_bf16(y[2], y[3]);
;         *(u32x2*)(xbf + (size_t)r * 1024 + i * 256 + lane * 4) = wv;
;       }
;     }
	v_pk_add_f32 v[66:67], v[18:19], v[20:21]
	v_pk_add_f32 v[68:69], v[22:23], v[24:25]
	v_pk_add_f32 v[70:71], v[26:27], v[28:29]
	v_pk_add_f32 v[72:73], v[30:31], v[32:33]
	v_pk_add_f32 v[66:67], v[66:67], v[68:69]
	v_pk_add_f32 v[70:71], v[70:71], v[72:73]
	v_pk_add_f32 v[66:67], v[66:67], v[70:71]
	v_add_f32_e32 v66, v66, v67
	s_nop 1
	v_add_f32_dpp v66, v66, v66 row_shr:1 row_mask:0xf bank_mask:0xf bound_ctrl:1
	s_nop 1
	v_add_f32_dpp v66, v66, v66 row_shr:2 row_mask:0xf bank_mask:0xf bound_ctrl:1
	s_nop 1
	v_add_f32_dpp v66, v66, v66 row_shr:4 row_mask:0xf bank_mask:0xf bound_ctrl:1
	s_nop 1
	v_add_f32_dpp v66, v66, v66 row_shr:8 row_mask:0xf bank_mask:0xf bound_ctrl:1
	s_nop 0
	v_readlane_b32 s9, v66, 15
	v_readlane_b32 s10, v66, 31
	v_readlane_b32 s11, v66, 47
	v_readlane_b32 vcc_lo, v66, 63
	s_nop 1
	v_mov_b32_e32 v66, s9
	v_add_f32_e32 v66, s10, v66
	v_add_f32_e32 v66, s11, v66
	v_add_f32_e32 v66, vcc_lo, v66
	v_mul_f32_e32 v116, 0x3a800000, v66
	v_mov_b32_e32 v117, v116
	v_pk_add_f32 v[18:19], v[18:19], v[116:117] neg_lo:[0,1] neg_hi:[0,1]
	v_pk_add_f32 v[20:21], v[20:21], v[116:117] neg_lo:[0,1] neg_hi:[0,1]
	v_pk_add_f32 v[22:23], v[22:23], v[116:117] neg_lo:[0,1] neg_hi:[0,1]
	v_pk_add_f32 v[24:25], v[24:25], v[116:117] neg_lo:[0,1] neg_hi:[0,1]
	v_pk_add_f32 v[26:27], v[26:27], v[116:117] neg_lo:[0,1] neg_hi:[0,1]
	v_pk_add_f32 v[28:29], v[28:29], v[116:117] neg_lo:[0,1] neg_hi:[0,1]
	v_pk_add_f32 v[30:31], v[30:31], v[116:117] neg_lo:[0,1] neg_hi:[0,1]
	v_pk_add_f32 v[32:33], v[32:33], v[116:117] neg_lo:[0,1] neg_hi:[0,1]
	v_pk_mul_f32 v[66:67], v[18:19], v[18:19]
	v_pk_mul_f32 v[68:69], v[20:21], v[20:21]
	v_pk_fma_f32 v[66:67], v[22:23], v[22:23], v[66:67]
	v_pk_fma_f32 v[68:69], v[24:25], v[24:25], v[68:69]
	v_pk_fma_f32 v[66:67], v[26:27], v[26:27], v[66:67]
	v_pk_fma_f32 v[68:69], v[28:29], v[28:29], v[68:69]
	v_pk_fma_f32 v[66:67], v[30:31], v[30:31], v[66:67]
	v_pk_fma_f32 v[68:69], v[32:33], v[32:33], v[68:69]
	v_pk_add_f32 v[66:67], v[66:67], v[68:69]
	v_add_f32_e32 v66, v66, v67
	s_nop 1
	v_add_f32_dpp v66, v66, v66 row_shr:1 row_mask:0xf bank_mask:0xf bound_ctrl:1
	s_nop 1
	v_add_f32_dpp v66, v66, v66 row_shr:2 row_mask:0xf bank_mask:0xf bound_ctrl:1
	s_nop 1
	v_add_f32_dpp v66, v66, v66 row_shr:4 row_mask:0xf bank_mask:0xf bound_ctrl:1
	s_nop 1
	v_add_f32_dpp v66, v66, v66 row_shr:8 row_mask:0xf bank_mask:0xf bound_ctrl:1
	s_nop 0
	v_readlane_b32 s9, v66, 15
	v_readlane_b32 s10, v66, 31
	v_readlane_b32 s11, v66, 47
	v_readlane_b32 vcc_lo, v66, 63
	s_nop 1
	v_mov_b32_e32 v66, s9
	v_add_f32_e32 v66, s10, v66
	v_add_f32_e32 v66, s11, v66
	v_add_f32_e32 v66, vcc_lo, v66
	v_mul_f32_e32 v66, 0x3a800000, v66
	v_add_f32_e32 v66, 0x3727c5ac, v66
	v_rsq_f32_e32 v118, v66
	s_nop 0
	v_mov_b32_e32 v119, v118
	v_pk_mul_f32 v[18:19], v[18:19], v[118:119]
	v_pk_mul_f32 v[20:21], v[20:21], v[118:119]
	v_pk_mul_f32 v[22:23], v[22:23], v[118:119]
	v_pk_mul_f32 v[24:25], v[24:25], v[118:119]
	v_pk_mul_f32 v[26:27], v[26:27], v[118:119]
	v_pk_mul_f32 v[28:29], v[28:29], v[118:119]
	v_pk_mul_f32 v[30:31], v[30:31], v[118:119]
	v_pk_mul_f32 v[32:33], v[32:33], v[118:119]
	v_pk_fma_f32 v[76:77], v[18:19], v[34:35], v[50:51]
	v_pk_fma_f32 v[78:79], v[20:21], v[36:37], v[52:53]
	v_pk_fma_f32 v[80:81], v[22:23], v[38:39], v[54:55]
	v_pk_fma_f32 v[82:83], v[24:25], v[40:41], v[56:57]
	v_pk_fma_f32 v[84:85], v[26:27], v[42:43], v[58:59]
	v_pk_fma_f32 v[86:87], v[28:29], v[44:45], v[60:61]
	v_pk_fma_f32 v[88:89], v[30:31], v[46:47], v[62:63]
	v_pk_fma_f32 v[90:91], v[32:33], v[48:49], v[64:65]
	v_cvt_pk_bf16_f32 v92, v76, v77
	v_cvt_pk_bf16_f32 v93, v78, v79
	v_cvt_pk_bf16_f32 v94, v80, v81
	v_cvt_pk_bf16_f32 v95, v82, v83
	v_cvt_pk_bf16_f32 v96, v84, v85
	v_cvt_pk_bf16_f32 v97, v86, v87
	v_cvt_pk_bf16_f32 v98, v88, v89
	v_cvt_pk_bf16_f32 v99, v90, v91
	global_store_dwordx2 v115, v[92:93], s[2:3] offset:0
	global_store_dwordx2 v115, v[94:95], s[2:3] offset:512
	global_store_dwordx2 v115, v[96:97], s[2:3] offset:1024
	global_store_dwordx2 v115, v[98:99], s[2:3] offset:1536
	s_add_u32 s2, s2, 0x400000
	s_addc_u32 s3, s3, 0
	s_add_u32 s0, s0, 0x800000
	s_addc_u32 s1, s1, 0
	global_load_dwordx4 v[18:21], v114, s[0:1] offset:0
	global_load_dwordx4 v[22:25], v114, s[0:1] offset:1024
	global_load_dwordx4 v[26:29], v114, s[0:1] offset:2048
	global_load_dwordx4 v[30:33], v114, s[0:1] offset:3072
	s_waitcnt vmcnt(8)
; __device__ __forceinline__ void phase_ln(float* R, const float* __restrict__ g, const float* __restrict__ b, bf16_t* xbf, float samp_scale, const float* __restrict__ part, int nsplit, bool f32_all) {
;     ...
;     float s = 0.f;
; #pragma unroll
;     for (int i = 0; i < 4; ++i) s += v[i][0] + v[i][1] + v[i][2] + v[i][3];
; #pragma unroll
;     for (int o = 32; o >= 1; o >>= 1) s += __shfl_xor(s, o);
;     const float mean = s * (1.f / 1024.f);
;     float ss = 0.f;
; #pragma unroll
;     for (int i = 0; i < 4; ++i) { v[i] = v[i] - mean; ss += v[i][0] * v[i][0] + v[i][1] * v[i][1] + v[i][2] * v[i][2] + v[i][3] * v[i][3]; }
; #pragma unroll
;     for (int o = 32; o >= 1; o >>= 1) ss += __shfl_xor(ss, o);
;     const float rstd = rsqrtf(ss * (1.f / 1024.f) + LN_EPS);
; #pragma unroll
;     for (int i = 0; i < 4; ++i) {
;       const f32x4 y = v[i] * rstd * gv[i] + bv[i];
;       if (r >= MP) *(f32x4*)(row + i * 256 + lane * 4) = y * samp_scale;
;       else if (f32_all) *(f32x4*)(row + i * 256 + lane * 4) = y;
;       if (xbf) {
;         u32x2 wv;
;         wv[0] = cvt_pk_bf16(y[0], y[1]); wv[1] = cvt_pk_bf16(y[2], y[3]);
;         *(u32x2*)(xbf + (size_t)r * 1024 + i * 256 + lane * 4) = wv;
;       }
;     }
	v_pk_add_f32 v[66:67], v[0:1], v[2:3]
	v_pk_add_f32 v[68:69], v[4:5], v[6:7]
	v_pk_add_f32 v[70:71], v[8:9], v[10:11]
	v_pk_add_f32 v[72:73], v[12:13], v[14:15]
	v_pk_add_f32 v[66:67], v[66:67], v[68:69]
	v_pk_add_f32 v[70:71], v[70:71], v[72:73]
	v_pk_add_f32 v[66:67], v[66:67], v[70:71]
	v_add_f32_e32 v66, v66, v67
	s_nop 1
	v_add_f32_dpp v66, v66, v66 row_shr:1 row_mask:0xf bank_mask:0xf bound_ctrl:1
	s_nop 1
	v_add_f32_dpp v66, v66, v66 row_shr:2 row_mask:0xf bank_mask:0xf bound_ctrl:1
	s_nop 1
	v_add_f32_dpp v66, v66, v66 row_shr:4 row_mask:0xf bank_mask:0xf bound_ctrl:1
	s_nop 1
	v_add_f32_dpp v66, v66, v66 row_shr:8 row_mask:0xf bank_mask:0xf bound_ctrl:1
	s_nop 0
	v_readlane_b32 s9, v66, 15
	v_readlane_b32 s10, v66, 31
	v_readlane_b32 s11, v66, 47
	v_readlane_b32 vcc_lo, v66, 63
	s_nop 1
	v_mov_b32_e32 v66, s9
	v_add_f32_e32 v66, s10, v66
	v_add_f32_e32 v66, s11, v66
	v_add_f32_e32 v66, vcc_lo, v66
	v_mul_f32_e32 v116, 0x3a800000, v66
	v_mov_b32_e32 v117, v116
	v_pk_add_f32 v[0:1], v[0:1], v[116:117] neg_lo:[0,1] neg_hi:[0,1]
	v_pk_add_f32 v[2:3], v[2:3], v[116:117] neg_lo:[0,1] neg_hi:[0,1]
	v_pk_add_f32 v[4:5], v[4:5], v[116:117] neg_lo:[0,1] neg_hi:[0,1]
	v_pk_add_f32 v[6:7], v[6:7], v[116:117] neg_lo:[0,1] neg_hi:[0,1]
	v_pk_add_f32 v[8:9], v[8:9], v[116:117] neg_lo:[0,1] neg_hi:[0,1]
	v_pk_add_f32 v[10:11], v[10:11], v[116:117] neg_lo:[0,1] neg_hi:[0,1]
	v_pk_add_f32 v[12:13], v[12:13], v[116:117] neg_lo:[0,1] neg_hi:[0,1]
	v_pk_add_f32 v[14:15], v[14:15], v[116:117] neg_lo:[0,1] neg_hi:[0,1]
	v_pk_mul_f32 v[66:67], v[0:1], v[0:1]
	v_pk_mul_f32 v[68:69], v[2:3], v[2:3]
	v_pk_fma_f32 v[66:67], v[4:5], v[4:5], v[66:67]
	v_pk_fma_f32 v[68:69], v[6:7], v[6:7], v[68:69]
	v_pk_fma_f32 v[66:67], v[8:9], v[8:9], v[66:67]
	v_pk_fma_f32 v[68:69], v[10:11], v[10:11], v[68:69]
	v_pk_fma_f32 v[66:67], v[12:13], v[12:13], v[66:67]
	v_pk_fma_f32 v[68:69], v[14:15], v[14:15], v[68:69]
	v_pk_add_f32 v[66:67], v[66:67], v[68:69]
	v_add_f32_e32 v66, v66, v67
	s_nop 1
	v_add_f32_dpp v66, v66, v66 row_shr:1 row_mask:0xf bank_mask:0xf bound_ctrl:1
	s_nop 1
	v_add_f32_dpp v66, v66, v66 row_shr:2 row_mask:0xf bank_mask:0xf bound_ctrl:1
	s_nop 1
	v_add_f32_dpp v66, v66, v66 row_shr:4 row_mask:0xf bank_mask:0xf bound_ctrl:1
	s_nop 1
	v_add_f32_dpp v66, v66, v66 row_shr:8 row_mask:0xf bank_mask:0xf bound_ctrl:1
	s_nop 0
	v_readlane_b32 s9, v66, 15
	v_readlane_b32 s10, v66, 31
	v_readlane_b32 s11, v66, 47
	v_readlane_b32 vcc_lo, v66, 63
	s_nop 1
	v_mov_b32_e32 v66, s9
	v_add_f32_e32 v66, s10, v66
	v_add_f32_e32 v66, s11, v66
	v_add_f32_e32 v66, vcc_lo, v66
	v_mul_f32_e32 v66, 0x3a800000, v66
	v_add_f32_e32 v66, 0x3727c5ac, v66
	v_rsq_f32_e32 v118, v66
	s_nop 0
	v_mov_b32_e32 v119, v118
	v_pk_mul_f32 v[0:1], v[0:1], v[118:119]
	v_pk_mul_f32 v[2:3], v[2:3], v[118:119]
	v_pk_mul_f32 v[4:5], v[4:5], v[118:119]
	v_pk_mul_f32 v[6:7], v[6:7], v[118:119]
	v_pk_mul_f32 v[8:9], v[8:9], v[118:119]
	v_pk_mul_f32 v[10:11], v[10:11], v[118:119]
	v_pk_mul_f32 v[12:13], v[12:13], v[118:119]
	v_pk_mul_f32 v[14:15], v[14:15], v[118:119]
	v_pk_fma_f32 v[76:77], v[0:1], v[34:35], v[50:51]
	v_pk_fma_f32 v[78:79], v[2:3], v[36:37], v[52:53]
	v_pk_fma_f32 v[80:81], v[4:5], v[38:39], v[54:55]
	v_pk_fma_f32 v[82:83], v[6:7], v[40:41], v[56:57]
	v_pk_fma_f32 v[84:85], v[8:9], v[42:43], v[58:59]
	v_pk_fma_f32 v[86:87], v[10:11], v[44:45], v[60:61]
	v_pk_fma_f32 v[88:89], v[12:13], v[46:47], v[62:63]
	v_pk_fma_f32 v[90:91], v[14:15], v[48:49], v[64:65]
	v_cvt_pk_bf16_f32 v92, v76, v77
	v_cvt_pk_bf16_f32 v93, v78, v79
	v_cvt_pk_bf16_f32 v94, v80, v81
	v_cvt_pk_bf16_f32 v95, v82, v83
	v_cvt_pk_bf16_f32 v96, v84, v85
	v_cvt_pk_bf16_f32 v97, v86, v87
	v_cvt_pk_bf16_f32 v98, v88, v89
	v_cvt_pk_bf16_f32 v99, v90, v91
	global_store_dwordx2 v115, v[92:93], s[2:3] offset:0
	global_store_dwordx2 v115, v[94:95], s[2:3] offset:512
	global_store_dwordx2 v115, v[96:97], s[2:3] offset:1024
	global_store_dwordx2 v115, v[98:99], s[2:3] offset:1536
	s_add_u32 s2, s2, 0x400000
	s_addc_u32 s3, s3, 0
	s_add_u32 s0, s0, 0x800000
	s_addc_u32 s1, s1, 0
	global_load_dwordx4 v[0:3], v114, s[0:1] offset:0
	global_load_dwordx4 v[4:7], v114, s[0:1] offset:1024
	global_load_dwordx4 v[8:11], v114, s[0:1] offset:2048
	global_load_dwordx4 v[12:15], v114, s[0:1] offset:3072
	s_waitcnt vmcnt(8)
; __device__ __forceinline__ void phase_ln(float* R, const float* __restrict__ g, const float* __restrict__ b, bf16_t* xbf, float samp_scale, const float* __restrict__ part, int nsplit, bool f32_all) {
;     ...
;     float s = 0.f;
; #pragma unroll
;     for (int i = 0; i < 4; ++i) s += v[i][0] + v[i][1] + v[i][2] + v[i][3];
; #pragma unroll
;     for (int o = 32; o >= 1; o >>= 1) s += __shfl_xor(s, o);
;     const float mean = s * (1.f / 1024.f);
;     float ss = 0.f;
; #pragma unroll
;     for (int i = 0; i < 4; ++i) { v[i] = v[i] - mean; ss += v[i][0] * v[i][0] + v[i][1] * v[i][1] + v[i][2] * v[i][2] + v[i][3] * v[i][3]; }
; #pragma unroll
;     for (int o = 32; o >= 1; o >>= 1) ss += __shfl_xor(ss, o);
;     const float rstd = rsqrtf(ss * (1.f / 1024.f) + LN_EPS);
; #pragma unroll
;     for (int i = 0; i < 4; ++i) {
;       const f32x4 y = v[i] * rstd * gv[i] + bv[i];
;       if (r >= MP) *(f32x4*)(row + i * 256 + lane * 4) = y * samp_scale;
;       else if (f32_all) *(f32x4*)(row + i * 256 + lane * 4) = y;
;       if (xbf) {
;         u32x2 wv;
;         wv[0] = cvt_pk_bf16(y[0], y[1]); wv[1] = cvt_pk_bf16(y[2], y[3]);
;         *(u32x2*)(xbf + (size_t)r * 1024 + i * 256 + lane * 4) = wv;
;       }
;     }
	v_pk_add_f32 v[66:67], v[18:19], v[20:21]
	v_pk_add_f32 v[68:69], v[22:23], v[24:25]
	v_pk_add_f32 v[70:71], v[26:27], v[28:29]
	v_pk_add_f32 v[72:73], v[30:31], v[32:33]
	v_pk_add_f32 v[66:67], v[66:67], v[68:69]
	v_pk_add_f32 v[70:71], v[70:71], v[72:73]
	v_pk_add_f32 v[66:67], v[66:67], v[70:71]
	v_add_f32_e32 v66, v66, v67
	s_nop 1
	v_add_f32_dpp v66, v66, v66 row_shr:1 row_mask:0xf bank_mask:0xf bound_ctrl:1
	s_nop 1
	v_add_f32_dpp v66, v66, v66 row_shr:2 row_mask:0xf bank_mask:0xf bound_ctrl:1
	s_nop 1
	v_add_f32_dpp v66, v66, v66 row_shr:4 row_mask:0xf bank_mask:0xf bound_ctrl:1
	s_nop 1
	v_add_f32_dpp v66, v66, v66 row_shr:8 row_mask:0xf bank_mask:0xf bound_ctrl:1
	s_nop 0
	v_readlane_b32 s9, v66, 15
	v_readlane_b32 s10, v66, 31
	v_readlane_b32 s11, v66, 47
	v_readlane_b32 vcc_lo, v66, 63
	s_nop 1
	v_mov_b32_e32 v66, s9
	v_add_f32_e32 v66, s10, v66
	v_add_f32_e32 v66, s11, v66
	v_add_f32_e32 v66, vcc_lo, v66
	v_mul_f32_e32 v116, 0x3a800000, v66
	v_mov_b32_e32 v117, v116
	v_pk_add_f32 v[18:19], v[18:19], v[116:117] neg_lo:[0,1] neg_hi:[0,1]
	v_pk_add_f32 v[20:21], v[20:21], v[116:117] neg_lo:[0,1] neg_hi:[0,1]
	v_pk_add_f32 v[22:23], v[22:23], v[116:117] neg_lo:[0,1] neg_hi:[0,1]
	v_pk_add_f32 v[24:25], v[24:25], v[116:117] neg_lo:[0,1] neg_hi:[0,1]
	v_pk_add_f32 v[26:27], v[26:27], v[116:117] neg_lo:[0,1] neg_hi:[0,1]
	v_pk_add_f32 v[28:29], v[28:29], v[116:117] neg_lo:[0,1] neg_hi:[0,1]
	v_pk_add_f32 v[30:31], v[30:31], v[116:117] neg_lo:[0,1] neg_hi:[0,1]
	v_pk_add_f32 v[32:33], v[32:33], v[116:117] neg_lo:[0,1] neg_hi:[0,1]
	v_pk_mul_f32 v[66:67], v[18:19], v[18:19]
	v_pk_mul_f32 v[68:69], v[20:21], v[20:21]
	v_pk_fma_f32 v[66:67], v[22:23], v[22:23], v[66:67]
	v_pk_fma_f32 v[68:69], v[24:25], v[24:25], v[68:69]
	v_pk_fma_f32 v[66:67], v[26:27], v[26:27], v[66:67]
	v_pk_fma_f32 v[68:69], v[28:29], v[28:29], v[68:69]
	v_pk_fma_f32 v[66:67], v[30:31], v[30:31], v[66:67]
	v_pk_fma_f32 v[68:69], v[32:33], v[32:33], v[68:69]
	v_pk_add_f32 v[66:67], v[66:67], v[68:69]
	v_add_f32_e32 v66, v66, v67
	s_nop 1
	v_add_f32_dpp v66, v66, v66 row_shr:1 row_mask:0xf bank_mask:0xf bound_ctrl:1
	s_nop 1
	v_add_f32_dpp v66, v66, v66 row_shr:2 row_mask:0xf bank_mask:0xf bound_ctrl:1
	s_nop 1
	v_add_f32_dpp v66, v66, v66 row_shr:4 row_mask:0xf bank_mask:0xf bound_ctrl:1
	s_nop 1
	v_add_f32_dpp v66, v66, v66 row_shr:8 row_mask:0xf bank_mask:0xf bound_ctrl:1
	s_nop 0
	v_readlane_b32 s9, v66, 15
	v_readlane_b32 s10, v66, 31
	v_readlane_b32 s11, v66, 47
	v_readlane_b32 vcc_lo, v66, 63
	s_nop 1
	v_mov_b32_e32 v66, s9
	v_add_f32_e32 v66, s10, v66
	v_add_f32_e32 v66, s11, v66
	v_add_f32_e32 v66, vcc_lo, v66
	v_mul_f32_e32 v66, 0x3a800000, v66
	v_add_f32_e32 v66, 0x3727c5ac, v66
	v_rsq_f32_e32 v118, v66
	s_nop 0
	v_mov_b32_e32 v119, v118
	v_pk_mul_f32 v[18:19], v[18:19], v[118:119]
	v_pk_mul_f32 v[20:21], v[20:21], v[118:119]
	v_pk_mul_f32 v[22:23], v[22:23], v[118:119]
	v_pk_mul_f32 v[24:25], v[24:25], v[118:119]
	v_pk_mul_f32 v[26:27], v[26:27], v[118:119]
	v_pk_mul_f32 v[28:29], v[28:29], v[118:119]
	v_pk_mul_f32 v[30:31], v[30:31], v[118:119]
	v_pk_mul_f32 v[32:33], v[32:33], v[118:119]
	v_pk_fma_f32 v[76:77], v[18:19], v[34:35], v[50:51]
	v_pk_fma_f32 v[78:79], v[20:21], v[36:37], v[52:53]
	v_pk_fma_f32 v[80:81], v[22:23], v[38:39], v[54:55]
	v_pk_fma_f32 v[82:83], v[24:25], v[40:41], v[56:57]
	v_pk_fma_f32 v[84:85], v[26:27], v[42:43], v[58:59]
	v_pk_fma_f32 v[86:87], v[28:29], v[44:45], v[60:61]
	v_pk_fma_f32 v[88:89], v[30:31], v[46:47], v[62:63]
	v_pk_fma_f32 v[90:91], v[32:33], v[48:49], v[64:65]
	v_cvt_pk_bf16_f32 v92, v76, v77
	v_cvt_pk_bf16_f32 v93, v78, v79
	v_cvt_pk_bf16_f32 v94, v80, v81
	v_cvt_pk_bf16_f32 v95, v82, v83
	v_cvt_pk_bf16_f32 v96, v84, v85
	v_cvt_pk_bf16_f32 v97, v86, v87
	v_cvt_pk_bf16_f32 v98, v88, v89
	v_cvt_pk_bf16_f32 v99, v90, v91
	global_store_dwordx2 v115, v[92:93], s[2:3] offset:0
	global_store_dwordx2 v115, v[94:95], s[2:3] offset:512
	global_store_dwordx2 v115, v[96:97], s[2:3] offset:1024
	global_store_dwordx2 v115, v[98:99], s[2:3] offset:1536
	s_add_u32 s2, s2, 0x400000
	s_addc_u32 s3, s3, 0
	s_add_u32 s0, s0, 0x800000
	s_addc_u32 s1, s1, 0
	global_load_dwordx4 v[18:21], v114, s[0:1] offset:0
	global_load_dwordx4 v[22:25], v114, s[0:1] offset:1024
	global_load_dwordx4 v[26:29], v114, s[0:1] offset:2048
	global_load_dwordx4 v[30:33], v114, s[0:1] offset:3072
	s_waitcnt vmcnt(8)
; __device__ __forceinline__ void phase_ln(float* R, const float* __restrict__ g, const float* __restrict__ b, bf16_t* xbf, float samp_scale, const float* __restrict__ part, int nsplit, bool f32_all) {
;     ...
;     float s = 0.f;
; #pragma unroll
;     for (int i = 0; i < 4; ++i) s += v[i][0] + v[i][1] + v[i][2] + v[i][3];
; #pragma unroll
;     for (int o = 32; o >= 1; o >>= 1) s += __shfl_xor(s, o);
;     const float mean = s * (1.f / 1024.f);
;     float ss = 0.f;
; #pragma unroll
;     for (int i = 0; i < 4; ++i) { v[i] = v[i] - mean; ss += v[i][0] * v[i][0] + v[i][1] * v[i][1] + v[i][2] * v[i][2] + v[i][3] * v[i][3]; }
; #pragma unroll
;     for (int o = 32; o >= 1; o >>= 1) ss += __shfl_xor(ss, o);
;     const float rstd = rsqrtf(ss * (1.f / 1024.f) + LN_EPS);
; #pragma unroll
;     for (int i = 0; i < 4; ++i) {
;       const f32x4 y = v[i] * rstd * gv[i] + bv[i];
;       if (r >= MP) *(f32x4*)(row + i * 256 + lane * 4) = y * samp_scale;
;       else if (f32_all) *(f32x4*)(row + i * 256 + lane * 4) = y;
;       if (xbf) {
;         u32x2 wv;
;         wv[0] = cvt_pk_bf16(y[0], y[1]); wv[1] = cvt_pk_bf16(y[2], y[3]);
;         *(u32x2*)(xbf + (size_t)r * 1024 + i * 256 + lane * 4) = wv;
;       }
;     }
	v_pk_add_f32 v[66:67], v[0:1], v[2:3]
	v_pk_add_f32 v[68:69], v[4:5], v[6:7]
	v_pk_add_f32 v[70:71], v[8:9], v[10:11]
	v_pk_add_f32 v[72:73], v[12:13], v[14:15]
	v_pk_add_f32 v[66:67], v[66:67], v[68:69]
	v_pk_add_f32 v[70:71], v[70:71], v[72:73]
	v_pk_add_f32 v[66:67], v[66:67], v[70:71]
	v_add_f32_e32 v66, v66, v67
	s_nop 1
	v_add_f32_dpp v66, v66, v66 row_shr:1 row_mask:0xf bank_mask:0xf bound_ctrl:1
	s_nop 1
	v_add_f32_dpp v66, v66, v66 row_shr:2 row_mask:0xf bank_mask:0xf bound_ctrl:1
	s_nop 1
	v_add_f32_dpp v66, v66, v66 row_shr:4 row_mask:0xf bank_mask:0xf bound_ctrl:1
	s_nop 1
	v_add_f32_dpp v66, v66, v66 row_shr:8 row_mask:0xf bank_mask:0xf bound_ctrl:1
	s_nop 0
	v_readlane_b32 s9, v66, 15
	v_readlane_b32 s10, v66, 31
	v_readlane_b32 s11, v66, 47
	v_readlane_b32 vcc_lo, v66, 63
	s_nop 1
	v_mov_b32_e32 v66, s9
	v_add_f32_e32 v66, s10, v66
	v_add_f32_e32 v66, s11, v66
	v_add_f32_e32 v66, vcc_lo, v66
	v_mul_f32_e32 v116, 0x3a800000, v66
	v_mov_b32_e32 v117, v116
	v_pk_add_f32 v[0:1], v[0:1], v[116:117] neg_lo:[0,1] neg_hi:[0,1]
	v_pk_add_f32 v[2:3], v[2:3], v[116:117] neg_lo:[0,1] neg_hi:[0,1]
	v_pk_add_f32 v[4:5], v[4:5], v[116:117] neg_lo:[0,1] neg_hi:[0,1]
	v_pk_add_f32 v[6:7], v[6:7], v[116:117] neg_lo:[0,1] neg_hi:[0,1]
	v_pk_add_f32 v[8:9], v[8:9], v[116:117] neg_lo:[0,1] neg_hi:[0,1]
	v_pk_add_f32 v[10:11], v[10:11], v[116:117] neg_lo:[0,1] neg_hi:[0,1]
	v_pk_add_f32 v[12:13], v[12:13], v[116:117] neg_lo:[0,1] neg_hi:[0,1]
	v_pk_add_f32 v[14:15], v[14:15], v[116:117] neg_lo:[0,1] neg_hi:[0,1]
	v_pk_mul_f32 v[66:67], v[0:1], v[0:1]
	v_pk_mul_f32 v[68:69], v[2:3], v[2:3]
	v_pk_fma_f32 v[66:67], v[4:5], v[4:5], v[66:67]
	v_pk_fma_f32 v[68:69], v[6:7], v[6:7], v[68:69]
	v_pk_fma_f32 v[66:67], v[8:9], v[8:9], v[66:67]
	v_pk_fma_f32 v[68:69], v[10:11], v[10:11], v[68:69]
	v_pk_fma_f32 v[66:67], v[12:13], v[12:13], v[66:67]
	v_pk_fma_f32 v[68:69], v[14:15], v[14:15], v[68:69]
	v_pk_add_f32 v[66:67], v[66:67], v[68:69]
	v_add_f32_e32 v66, v66, v67
	s_nop 1
	v_add_f32_dpp v66, v66, v66 row_shr:1 row_mask:0xf bank_mask:0xf bound_ctrl:1
	s_nop 1
	v_add_f32_dpp v66, v66, v66 row_shr:2 row_mask:0xf bank_mask:0xf bound_ctrl:1
	s_nop 1
	v_add_f32_dpp v66, v66, v66 row_shr:4 row_mask:0xf bank_mask:0xf bound_ctrl:1
	s_nop 1
	v_add_f32_dpp v66, v66, v66 row_shr:8 row_mask:0xf bank_mask:0xf bound_ctrl:1
	s_nop 0
	v_readlane_b32 s9, v66, 15
	v_readlane_b32 s10, v66, 31
	v_readlane_b32 s11, v66, 47
	v_readlane_b32 vcc_lo, v66, 63
	s_nop 1
	v_mov_b32_e32 v66, s9
	v_add_f32_e32 v66, s10, v66
	v_add_f32_e32 v66, s11, v66
	v_add_f32_e32 v66, vcc_lo, v66
	v_mul_f32_e32 v66, 0x3a800000, v66
	v_add_f32_e32 v66, 0x3727c5ac, v66
	v_rsq_f32_e32 v118, v66
	s_nop 0
	v_mov_b32_e32 v119, v118
	v_pk_mul_f32 v[0:1], v[0:1], v[118:119]
	v_pk_mul_f32 v[2:3], v[2:3], v[118:119]
	v_pk_mul_f32 v[4:5], v[4:5], v[118:119]
	v_pk_mul_f32 v[6:7], v[6:7], v[118:119]
	v_pk_mul_f32 v[8:9], v[8:9], v[118:119]
	v_pk_mul_f32 v[10:11], v[10:11], v[118:119]
	v_pk_mul_f32 v[12:13], v[12:13], v[118:119]
	v_pk_mul_f32 v[14:15], v[14:15], v[118:119]
	v_pk_fma_f32 v[76:77], v[0:1], v[34:35], v[50:51]
	v_pk_fma_f32 v[78:79], v[2:3], v[36:37], v[52:53]
	v_pk_fma_f32 v[80:81], v[4:5], v[38:39], v[54:55]
	v_pk_fma_f32 v[82:83], v[6:7], v[40:41], v[56:57]
	v_pk_fma_f32 v[84:85], v[8:9], v[42:43], v[58:59]
	v_pk_fma_f32 v[86:87], v[10:11], v[44:45], v[60:61]
	v_pk_fma_f32 v[88:89], v[12:13], v[46:47], v[62:63]
	v_pk_fma_f32 v[90:91], v[14:15], v[48:49], v[64:65]
	v_cvt_pk_bf16_f32 v92, v76, v77
	v_cvt_pk_bf16_f32 v93, v78, v79
	v_cvt_pk_bf16_f32 v94, v80, v81
	v_cvt_pk_bf16_f32 v95, v82, v83
	v_cvt_pk_bf16_f32 v96, v84, v85
	v_cvt_pk_bf16_f32 v97, v86, v87
	v_cvt_pk_bf16_f32 v98, v88, v89
	v_cvt_pk_bf16_f32 v99, v90, v91
	global_store_dwordx2 v115, v[92:93], s[2:3] offset:0
	global_store_dwordx2 v115, v[94:95], s[2:3] offset:512
	global_store_dwordx2 v115, v[96:97], s[2:3] offset:1024
	global_store_dwordx2 v115, v[98:99], s[2:3] offset:1536
	s_add_u32 s2, s2, 0x400000
	s_addc_u32 s3, s3, 0
	s_add_u32 s0, s0, 0x800000
	s_addc_u32 s1, s1, 0
	global_load_dwordx4 v[0:3], v114, s[0:1] offset:0
	global_load_dwordx4 v[4:7], v114, s[0:1] offset:1024
	global_load_dwordx4 v[8:11], v114, s[0:1] offset:2048
	global_load_dwordx4 v[12:15], v114, s[0:1] offset:3072
	s_waitcnt vmcnt(8)
; __device__ __forceinline__ void phase_ln(float* R, const float* __restrict__ g, const float* __restrict__ b, bf16_t* xbf, float samp_scale, const float* __restrict__ part, int nsplit, bool f32_all) {
;     ...
;     float s = 0.f;
; #pragma unroll
;     for (int i = 0; i < 4; ++i) s += v[i][0] + v[i][1] + v[i][2] + v[i][3];
; #pragma unroll
;     for (int o = 32; o >= 1; o >>= 1) s += __shfl_xor(s, o);
;     const float mean = s * (1.f / 1024.f);
;     float ss = 0.f;
; #pragma unroll
;     for (int i = 0; i < 4; ++i) { v[i] = v[i] - mean; ss += v[i][0] * v[i][0] + v[i][1] * v[i][1] + v[i][2] * v[i][2] + v[i][3] * v[i][3]; }
; #pragma unroll
;     for (int o = 32; o >= 1; o >>= 1) ss += __shfl_xor(ss, o);
;     const float rstd = rsqrtf(ss * (1.f / 1024.f) + LN_EPS);
; #pragma unroll
;     for (int i = 0; i < 4; ++i) {
;       const f32x4 y = v[i] * rstd * gv[i] + bv[i];
;       if (r >= MP) *(f32x4*)(row + i * 256 + lane * 4) = y * samp_scale;
;       else if (f32_all) *(f32x4*)(row + i * 256 + lane * 4) = y;
;       if (xbf) {
;         u32x2 wv;
;         wv[0] = cvt_pk_bf16(y[0], y[1]); wv[1] = cvt_pk_bf16(y[2], y[3]);
;         *(u32x2*)(xbf + (size_t)r * 1024 + i * 256 + lane * 4) = wv;
;       }
;     }
	v_pk_add_f32 v[66:67], v[18:19], v[20:21]
	v_pk_add_f32 v[68:69], v[22:23], v[24:25]
	v_pk_add_f32 v[70:71], v[26:27], v[28:29]
	v_pk_add_f32 v[72:73], v[30:31], v[32:33]
	v_pk_add_f32 v[66:67], v[66:67], v[68:69]
	v_pk_add_f32 v[70:71], v[70:71], v[72:73]
	v_pk_add_f32 v[66:67], v[66:67], v[70:71]
	v_add_f32_e32 v66, v66, v67
	s_nop 1
	v_add_f32_dpp v66, v66, v66 row_shr:1 row_mask:0xf bank_mask:0xf bound_ctrl:1
	s_nop 1
	v_add_f32_dpp v66, v66, v66 row_shr:2 row_mask:0xf bank_mask:0xf bound_ctrl:1
	s_nop 1
	v_add_f32_dpp v66, v66, v66 row_shr:4 row_mask:0xf bank_mask:0xf bound_ctrl:1
	s_nop 1
	v_add_f32_dpp v66, v66, v66 row_shr:8 row_mask:0xf bank_mask:0xf bound_ctrl:1
	s_nop 0
	v_readlane_b32 s9, v66, 15
	v_readlane_b32 s10, v66, 31
	v_readlane_b32 s11, v66, 47
	v_readlane_b32 vcc_lo, v66, 63
	s_nop 1
	v_mov_b32_e32 v66, s9
	v_add_f32_e32 v66, s10, v66
	v_add_f32_e32 v66, s11, v66
	v_add_f32_e32 v66, vcc_lo, v66
	v_mul_f32_e32 v116, 0x3a800000, v66
	v_mov_b32_e32 v117, v116
	v_pk_add_f32 v[18:19], v[18:19], v[116:117] neg_lo:[0,1] neg_hi:[0,1]
	v_pk_add_f32 v[20:21], v[20:21], v[116:117] neg_lo:[0,1] neg_hi:[0,1]
	v_pk_add_f32 v[22:23], v[22:23], v[116:117] neg_lo:[0,1] neg_hi:[0,1]
	v_pk_add_f32 v[24:25], v[24:25], v[116:117] neg_lo:[0,1] neg_hi:[0,1]
	v_pk_add_f32 v[26:27], v[26:27], v[116:117] neg_lo:[0,1] neg_hi:[0,1]
	v_pk_add_f32 v[28:29], v[28:29], v[116:117] neg_lo:[0,1] neg_hi:[0,1]
	v_pk_add_f32 v[30:31], v[30:31], v[116:117] neg_lo:[0,1] neg_hi:[0,1]
	v_pk_add_f32 v[32:33], v[32:33], v[116:117] neg_lo:[0,1] neg_hi:[0,1]
	v_pk_mul_f32 v[66:67], v[18:19], v[18:19]
	v_pk_mul_f32 v[68:69], v[20:21], v[20:21]
	v_pk_fma_f32 v[66:67], v[22:23], v[22:23], v[66:67]
	v_pk_fma_f32 v[68:69], v[24:25], v[24:25], v[68:69]
	v_pk_fma_f32 v[66:67], v[26:27], v[26:27], v[66:67]
	v_pk_fma_f32 v[68:69], v[28:29], v[28:29], v[68:69]
	v_pk_fma_f32 v[66:67], v[30:31], v[30:31], v[66:67]
	v_pk_fma_f32 v[68:69], v[32:33], v[32:33], v[68:69]
	v_pk_add_f32 v[66:67], v[66:67], v[68:69]
	v_add_f32_e32 v66, v66, v67
	s_nop 1
	v_add_f32_dpp v66, v66, v66 row_shr:1 row_mask:0xf bank_mask:0xf bound_ctrl:1
	s_nop 1
	v_add_f32_dpp v66, v66, v66 row_shr:2 row_mask:0xf bank_mask:0xf bound_ctrl:1
	s_nop 1
	v_add_f32_dpp v66, v66, v66 row_shr:4 row_mask:0xf bank_mask:0xf bound_ctrl:1
	s_nop 1
	v_add_f32_dpp v66, v66, v66 row_shr:8 row_mask:0xf bank_mask:0xf bound_ctrl:1
	s_nop 0
	v_readlane_b32 s9, v66, 15
	v_readlane_b32 s10, v66, 31
	v_readlane_b32 s11, v66, 47
	v_readlane_b32 vcc_lo, v66, 63
	s_nop 1
	v_mov_b32_e32 v66, s9
	v_add_f32_e32 v66, s10, v66
	v_add_f32_e32 v66, s11, v66
	v_add_f32_e32 v66, vcc_lo, v66
	v_mul_f32_e32 v66, 0x3a800000, v66
	v_add_f32_e32 v66, 0x3727c5ac, v66
	v_rsq_f32_e32 v118, v66
	s_nop 0
	v_mov_b32_e32 v119, v118
	v_pk_mul_f32 v[18:19], v[18:19], v[118:119]
	v_pk_mul_f32 v[20:21], v[20:21], v[118:119]
	v_pk_mul_f32 v[22:23], v[22:23], v[118:119]
	v_pk_mul_f32 v[24:25], v[24:25], v[118:119]
	v_pk_mul_f32 v[26:27], v[26:27], v[118:119]
	v_pk_mul_f32 v[28:29], v[28:29], v[118:119]
	v_pk_mul_f32 v[30:31], v[30:31], v[118:119]
	v_pk_mul_f32 v[32:33], v[32:33], v[118:119]
	v_pk_fma_f32 v[76:77], v[18:19], v[34:35], v[50:51]
	v_pk_fma_f32 v[78:79], v[20:21], v[36:37], v[52:53]
	v_pk_fma_f32 v[80:81], v[22:23], v[38:39], v[54:55]
	v_pk_fma_f32 v[82:83], v[24:25], v[40:41], v[56:57]
	v_pk_fma_f32 v[84:85], v[26:27], v[42:43], v[58:59]
	v_pk_fma_f32 v[86:87], v[28:29], v[44:45], v[60:61]
	v_pk_fma_f32 v[88:89], v[30:31], v[46:47], v[62:63]
	v_pk_fma_f32 v[90:91], v[32:33], v[48:49], v[64:65]
	v_cvt_pk_bf16_f32 v92, v76, v77
	v_cvt_pk_bf16_f32 v93, v78, v79
	v_cvt_pk_bf16_f32 v94, v80, v81
	v_cvt_pk_bf16_f32 v95, v82, v83
	v_cvt_pk_bf16_f32 v96, v84, v85
	v_cvt_pk_bf16_f32 v97, v86, v87
	v_cvt_pk_bf16_f32 v98, v88, v89
	v_cvt_pk_bf16_f32 v99, v90, v91
	global_store_dwordx2 v115, v[92:93], s[2:3] offset:0
	global_store_dwordx2 v115, v[94:95], s[2:3] offset:512
	global_store_dwordx2 v115, v[96:97], s[2:3] offset:1024
	global_store_dwordx2 v115, v[98:99], s[2:3] offset:1536
	s_add_u32 s2, s2, 0x400000
	s_addc_u32 s3, s3, 0
	s_add_u32 s0, s0, 0x800000
	s_addc_u32 s1, s1, 0
	global_load_dwordx4 v[18:21], v114, s[0:1] offset:0
	global_load_dwordx4 v[22:25], v114, s[0:1] offset:1024
	global_load_dwordx4 v[26:29], v114, s[0:1] offset:2048
	global_load_dwordx4 v[30:33], v114, s[0:1] offset:3072
	s_waitcnt vmcnt(8)
; __device__ __forceinline__ void phase_ln(float* R, const float* __restrict__ g, const float* __restrict__ b, bf16_t* xbf, float samp_scale, const float* __restrict__ part, int nsplit, bool f32_all) {
;     ...
;   for (int r = gw; r < MT; r += nw) {
;     float* row = R + (size_t)r * 1024;
;     f32x4 v[4];
; #pragma unroll
;     for (int i = 0; i < 4; ++i) v[i] = *(const f32x4*)(row + i * 256 + lane * 4);
;     if (r >= MP) {
;       for (int sp = 0; sp < nsplit; ++sp) {
;         const float* prow = part + ((size_t)sp * MS + (r - MP)) * 1024;
; #pragma unroll
;         for (int i = 0; i < 4; ++i) v[i] = v[i] + *(const f32x4*)(prow + i * 256 + lane * 4);
;       }
;     }
;     float s = 0.f;
; #pragma unroll
;     for (int i = 0; i < 4; ++i) s += v[i][0] + v[i][1] + v[i][2] + v[i][3];
; #pragma unroll
;     for (int o = 32; o >= 1; o >>= 1) s += __shfl_xor(s, o);
;     const float mean = s * (1.f / 1024.f);
;     float ss = 0.f;
; #pragma unroll
;     for (int i = 0; i < 4; ++i) { v[i] = v[i] - mean; ss += v[i][0] * v[i][0] + v[i][1] * v[i][1] + v[i][2] * v[i][2] + v[i][3] * v[i][3]; }
; #pragma unroll
;     for (int o = 32; o >= 1; o >>= 1) ss += __shfl_xor(ss, o);
;     const float rstd = rsqrtf(ss * (1.f / 1024.f) + LN_EPS);
; #pragma unroll
;     for (int i = 0; i < 4; ++i) {
;       const f32x4 y = v[i] * rstd * gv[i] + bv[i];
;       if (r >= MP) *(f32x4*)(row + i * 256 + lane * 4) = y * samp_scale;
;       else if (f32_all) *(f32x4*)(row + i * 256 + lane * 4) = y;
;       if (xbf) {
;         u32x2 wv;
;         wv[0] = cvt_pk_bf16(y[0], y[1]); wv[1] = cvt_pk_bf16(y[2], y[3]);
;         *(u32x2*)(xbf + (size_t)r * 1024 + i * 256 + lane * 4) = wv;
;       }
;     }
	v_pk_add_f32 v[66:67], v[0:1], v[2:3]
	v_pk_add_f32 v[68:69], v[4:5], v[6:7]
	v_pk_add_f32 v[70:71], v[8:9], v[10:11]
	v_pk_add_f32 v[72:73], v[12:13], v[14:15]
	v_pk_add_f32 v[66:67], v[66:67], v[68:69]
	v_pk_add_f32 v[70:71], v[70:71], v[72:73]
	v_pk_add_f32 v[66:67], v[66:67], v[70:71]
	v_add_f32_e32 v66, v66, v67
	s_nop 1
	v_add_f32_dpp v66, v66, v66 row_shr:1 row_mask:0xf bank_mask:0xf bound_ctrl:1
	s_nop 1
	v_add_f32_dpp v66, v66, v66 row_shr:2 row_mask:0xf bank_mask:0xf bound_ctrl:1
	s_nop 1
	v_add_f32_dpp v66, v66, v66 row_shr:4 row_mask:0xf bank_mask:0xf bound_ctrl:1
	s_nop 1
	v_add_f32_dpp v66, v66, v66 row_shr:8 row_mask:0xf bank_mask:0xf bound_ctrl:1
	s_nop 0
	v_readlane_b32 s9, v66, 15
	v_readlane_b32 s10, v66, 31
	v_readlane_b32 s11, v66, 47
	v_readlane_b32 vcc_lo, v66, 63
	s_nop 1
	v_mov_b32_e32 v66, s9
	v_add_f32_e32 v66, s10, v66
	v_add_f32_e32 v66, s11, v66
	v_add_f32_e32 v66, vcc_lo, v66
	v_mul_f32_e32 v116, 0x3a800000, v66
	v_mov_b32_e32 v117, v116
	v_pk_add_f32 v[0:1], v[0:1], v[116:117] neg_lo:[0,1] neg_hi:[0,1]
	v_pk_add_f32 v[2:3], v[2:3], v[116:117] neg_lo:[0,1] neg_hi:[0,1]
	v_pk_add_f32 v[4:5], v[4:5], v[116:117] neg_lo:[0,1] neg_hi:[0,1]
	v_pk_add_f32 v[6:7], v[6:7], v[116:117] neg_lo:[0,1] neg_hi:[0,1]
	v_pk_add_f32 v[8:9], v[8:9], v[116:117] neg_lo:[0,1] neg_hi:[0,1]
	v_pk_add_f32 v[10:11], v[10:11], v[116:117] neg_lo:[0,1] neg_hi:[0,1]
	v_pk_add_f32 v[12:13], v[12:13], v[116:117] neg_lo:[0,1] neg_hi:[0,1]
	v_pk_add_f32 v[14:15], v[14:15], v[116:117] neg_lo:[0,1] neg_hi:[0,1]
	v_pk_mul_f32 v[66:67], v[0:1], v[0:1]
	v_pk_mul_f32 v[68:69], v[2:3], v[2:3]
	v_pk_fma_f32 v[66:67], v[4:5], v[4:5], v[66:67]
	v_pk_fma_f32 v[68:69], v[6:7], v[6:7], v[68:69]
	v_pk_fma_f32 v[66:67], v[8:9], v[8:9], v[66:67]
	v_pk_fma_f32 v[68:69], v[10:11], v[10:11], v[68:69]
	v_pk_fma_f32 v[66:67], v[12:13], v[12:13], v[66:67]
	v_pk_fma_f32 v[68:69], v[14:15], v[14:15], v[68:69]
	v_pk_add_f32 v[66:67], v[66:67], v[68:69]
	v_add_f32_e32 v66, v66, v67
	s_nop 1
	v_add_f32_dpp v66, v66, v66 row_shr:1 row_mask:0xf bank_mask:0xf bound_ctrl:1
	s_nop 1
	v_add_f32_dpp v66, v66, v66 row_shr:2 row_mask:0xf bank_mask:0xf bound_ctrl:1
	s_nop 1
	v_add_f32_dpp v66, v66, v66 row_shr:4 row_mask:0xf bank_mask:0xf bound_ctrl:1
	s_nop 1
	v_add_f32_dpp v66, v66, v66 row_shr:8 row_mask:0xf bank_mask:0xf bound_ctrl:1
	s_nop 0
	v_readlane_b32 s9, v66, 15
	v_readlane_b32 s10, v66, 31
	v_readlane_b32 s11, v66, 47
	v_readlane_b32 vcc_lo, v66, 63
	s_nop 1
	v_mov_b32_e32 v66, s9
	v_add_f32_e32 v66, s10, v66
	v_add_f32_e32 v66, s11, v66
	v_add_f32_e32 v66, vcc_lo, v66
	v_mul_f32_e32 v66, 0x3a800000, v66
	v_add_f32_e32 v66, 0x3727c5ac, v66
	v_rsq_f32_e32 v118, v66
	s_nop 0
	v_mov_b32_e32 v119, v118
	v_pk_mul_f32 v[0:1], v[0:1], v[118:119]
	v_pk_mul_f32 v[2:3], v[2:3], v[118:119]
	v_pk_mul_f32 v[4:5], v[4:5], v[118:119]
	v_pk_mul_f32 v[6:7], v[6:7], v[118:119]
	v_pk_mul_f32 v[8:9], v[8:9], v[118:119]
	v_pk_mul_f32 v[10:11], v[10:11], v[118:119]
	v_pk_mul_f32 v[12:13], v[12:13], v[118:119]
	v_pk_mul_f32 v[14:15], v[14:15], v[118:119]
	v_pk_fma_f32 v[76:77], v[0:1], v[34:35], v[50:51]
	v_pk_fma_f32 v[78:79], v[2:3], v[36:37], v[52:53]
	v_pk_fma_f32 v[80:81], v[4:5], v[38:39], v[54:55]
	v_pk_fma_f32 v[82:83], v[6:7], v[40:41], v[56:57]
	v_pk_fma_f32 v[84:85], v[8:9], v[42:43], v[58:59]
	v_pk_fma_f32 v[86:87], v[10:11], v[44:45], v[60:61]
	v_pk_fma_f32 v[88:89], v[12:13], v[46:47], v[62:63]
	v_pk_fma_f32 v[90:91], v[14:15], v[48:49], v[64:65]
	v_cvt_pk_bf16_f32 v92, v76, v77
	v_cvt_pk_bf16_f32 v93, v78, v79
	v_cvt_pk_bf16_f32 v94, v80, v81
	v_cvt_pk_bf16_f32 v95, v82, v83
	v_cvt_pk_bf16_f32 v96, v84, v85
	v_cvt_pk_bf16_f32 v97, v86, v87
	v_cvt_pk_bf16_f32 v98, v88, v89
	v_cvt_pk_bf16_f32 v99, v90, v91
	global_store_dwordx2 v115, v[92:93], s[2:3] offset:0
	global_store_dwordx2 v115, v[94:95], s[2:3] offset:512
	global_store_dwordx2 v115, v[96:97], s[2:3] offset:1024
	global_store_dwordx2 v115, v[98:99], s[2:3] offset:1536
	s_add_u32 s2, s2, 0x400000
	s_addc_u32 s3, s3, 0
	s_add_u32 s0, s0, 0x800000
	s_addc_u32 s1, s1, 0
	global_load_dwordx4 v[0:3], v114, s[0:1] offset:0
	global_load_dwordx4 v[4:7], v114, s[0:1] offset:1024
	global_load_dwordx4 v[8:11], v114, s[0:1] offset:2048
	global_load_dwordx4 v[12:15], v114, s[0:1] offset:3072
	s_waitcnt vmcnt(8)
; __device__ __forceinline__ void phase_ln(float* R, const float* __restrict__ g, const float* __restrict__ b, bf16_t* xbf, float samp_scale, const float* __restrict__ part, int nsplit, bool f32_all) {
;     ...
;   for (int r = gw; r < MT; r += nw) {
;     float* row = R + (size_t)r * 1024;
;     f32x4 v[4];
; #pragma unroll
;     for (int i = 0; i < 4; ++i) v[i] = *(const f32x4*)(row + i * 256 + lane * 4);
;     if (r >= MP) {
;       for (int sp = 0; sp < nsplit; ++sp) {
;         const float* prow = part + ((size_t)sp * MS + (r - MP)) * 1024;
; #pragma unroll
;         for (int i = 0; i < 4; ++i) v[i] = v[i] + *(const f32x4*)(prow + i * 256 + lane * 4);
;       }
;     }
;     float s = 0.f;
; #pragma unroll
;     for (int i = 0; i < 4; ++i) s += v[i][0] + v[i][1] + v[i][2] + v[i][3];
; #pragma unroll
;     for (int o = 32; o >= 1; o >>= 1) s += __shfl_xor(s, o);
;     const float mean = s * (1.f / 1024.f);
;     float ss = 0.f;
; #pragma unroll
;     for (int i = 0; i < 4; ++i) { v[i] = v[i] - mean; ss += v[i][0] * v[i][0] + v[i][1] * v[i][1] + v[i][2] * v[i][2] + v[i][3] * v[i][3]; }
; #pragma unroll
;     for (int o = 32; o >= 1; o >>= 1) ss += __shfl_xor(ss, o);
;     const float rstd = rsqrtf(ss * (1.f / 1024.f) + LN_EPS);
; #pragma unroll
;     for (int i = 0; i < 4; ++i) {
;       const f32x4 y = v[i] * rstd * gv[i] + bv[i];
;       if (r >= MP) *(f32x4*)(row + i * 256 + lane * 4) = y * samp_scale;
;       else if (f32_all) *(f32x4*)(row + i * 256 + lane * 4) = y;
;       if (xbf) {
;         u32x2 wv;
;         wv[0] = cvt_pk_bf16(y[0], y[1]); wv[1] = cvt_pk_bf16(y[2], y[3]);
;         *(u32x2*)(xbf + (size_t)r * 1024 + i * 256 + lane * 4) = wv;
;       }
;     }
	v_pk_add_f32 v[66:67], v[18:19], v[20:21]
	v_pk_add_f32 v[68:69], v[22:23], v[24:25]
	v_pk_add_f32 v[70:71], v[26:27], v[28:29]
	v_pk_add_f32 v[72:73], v[30:31], v[32:33]
	v_pk_add_f32 v[66:67], v[66:67], v[68:69]
	v_pk_add_f32 v[70:71], v[70:71], v[72:73]
	v_pk_add_f32 v[66:67], v[66:67], v[70:71]
	v_add_f32_e32 v66, v66, v67
	s_nop 1
	v_add_f32_dpp v66, v66, v66 row_shr:1 row_mask:0xf bank_mask:0xf bound_ctrl:1
	s_nop 1
	v_add_f32_dpp v66, v66, v66 row_shr:2 row_mask:0xf bank_mask:0xf bound_ctrl:1
	s_nop 1
	v_add_f32_dpp v66, v66, v66 row_shr:4 row_mask:0xf bank_mask:0xf bound_ctrl:1
	s_nop 1
	v_add_f32_dpp v66, v66, v66 row_shr:8 row_mask:0xf bank_mask:0xf bound_ctrl:1
	s_nop 0
	v_readlane_b32 s9, v66, 15
	v_readlane_b32 s10, v66, 31
	v_readlane_b32 s11, v66, 47
	v_readlane_b32 vcc_lo, v66, 63
	s_nop 1
	v_mov_b32_e32 v66, s9
	v_add_f32_e32 v66, s10, v66
	v_add_f32_e32 v66, s11, v66
	v_add_f32_e32 v66, vcc_lo, v66
	v_mul_f32_e32 v116, 0x3a800000, v66
	v_mov_b32_e32 v117, v116
	v_pk_add_f32 v[18:19], v[18:19], v[116:117] neg_lo:[0,1] neg_hi:[0,1]
	v_pk_add_f32 v[20:21], v[20:21], v[116:117] neg_lo:[0,1] neg_hi:[0,1]
	v_pk_add_f32 v[22:23], v[22:23], v[116:117] neg_lo:[0,1] neg_hi:[0,1]
	v_pk_add_f32 v[24:25], v[24:25], v[116:117] neg_lo:[0,1] neg_hi:[0,1]
	v_pk_add_f32 v[26:27], v[26:27], v[116:117] neg_lo:[0,1] neg_hi:[0,1]
	v_pk_add_f32 v[28:29], v[28:29], v[116:117] neg_lo:[0,1] neg_hi:[0,1]
	v_pk_add_f32 v[30:31], v[30:31], v[116:117] neg_lo:[0,1] neg_hi:[0,1]
	v_pk_add_f32 v[32:33], v[32:33], v[116:117] neg_lo:[0,1] neg_hi:[0,1]
	v_pk_mul_f32 v[66:67], v[18:19], v[18:19]
	v_pk_mul_f32 v[68:69], v[20:21], v[20:21]
	v_pk_fma_f32 v[66:67], v[22:23], v[22:23], v[66:67]
	v_pk_fma_f32 v[68:69], v[24:25], v[24:25], v[68:69]
	v_pk_fma_f32 v[66:67], v[26:27], v[26:27], v[66:67]
	v_pk_fma_f32 v[68:69], v[28:29], v[28:29], v[68:69]
	v_pk_fma_f32 v[66:67], v[30:31], v[30:31], v[66:67]
	v_pk_fma_f32 v[68:69], v[32:33], v[32:33], v[68:69]
	v_pk_add_f32 v[66:67], v[66:67], v[68:69]
	v_add_f32_e32 v66, v66, v67
	s_nop 1
	v_add_f32_dpp v66, v66, v66 row_shr:1 row_mask:0xf bank_mask:0xf bound_ctrl:1
	s_nop 1
	v_add_f32_dpp v66, v66, v66 row_shr:2 row_mask:0xf bank_mask:0xf bound_ctrl:1
	s_nop 1
	v_add_f32_dpp v66, v66, v66 row_shr:4 row_mask:0xf bank_mask:0xf bound_ctrl:1
	s_nop 1
	v_add_f32_dpp v66, v66, v66 row_shr:8 row_mask:0xf bank_mask:0xf bound_ctrl:1
	s_nop 0
	v_readlane_b32 s9, v66, 15
	v_readlane_b32 s10, v66, 31
	v_readlane_b32 s11, v66, 47
	v_readlane_b32 vcc_lo, v66, 63
	s_nop 1
	v_mov_b32_e32 v66, s9
	v_add_f32_e32 v66, s10, v66
	v_add_f32_e32 v66, s11, v66
	v_add_f32_e32 v66, vcc_lo, v66
	v_mul_f32_e32 v66, 0x3a800000, v66
	v_add_f32_e32 v66, 0x3727c5ac, v66
	v_rsq_f32_e32 v118, v66
	s_nop 0
	v_mov_b32_e32 v119, v118
	v_pk_mul_f32 v[18:19], v[18:19], v[118:119]
	v_pk_mul_f32 v[20:21], v[20:21], v[118:119]
	v_pk_mul_f32 v[22:23], v[22:23], v[118:119]
	v_pk_mul_f32 v[24:25], v[24:25], v[118:119]
	v_pk_mul_f32 v[26:27], v[26:27], v[118:119]
	v_pk_mul_f32 v[28:29], v[28:29], v[118:119]
	v_pk_mul_f32 v[30:31], v[30:31], v[118:119]
	v_pk_mul_f32 v[32:33], v[32:33], v[118:119]
	v_pk_fma_f32 v[76:77], v[18:19], v[34:35], v[50:51]
	v_pk_fma_f32 v[78:79], v[20:21], v[36:37], v[52:53]
	v_pk_fma_f32 v[80:81], v[22:23], v[38:39], v[54:55]
	v_pk_fma_f32 v[82:83], v[24:25], v[40:41], v[56:57]
	v_pk_fma_f32 v[84:85], v[26:27], v[42:43], v[58:59]
	v_pk_fma_f32 v[86:87], v[28:29], v[44:45], v[60:61]
	v_pk_fma_f32 v[88:89], v[30:31], v[46:47], v[62:63]
	v_pk_fma_f32 v[90:91], v[32:33], v[48:49], v[64:65]
	v_cvt_pk_bf16_f32 v92, v76, v77
	v_cvt_pk_bf16_f32 v93, v78, v79
	v_cvt_pk_bf16_f32 v94, v80, v81
	v_cvt_pk_bf16_f32 v95, v82, v83
	v_cvt_pk_bf16_f32 v96, v84, v85
	v_cvt_pk_bf16_f32 v97, v86, v87
	v_cvt_pk_bf16_f32 v98, v88, v89
	v_cvt_pk_bf16_f32 v99, v90, v91
	global_store_dwordx2 v115, v[92:93], s[2:3] offset:0
	global_store_dwordx2 v115, v[94:95], s[2:3] offset:512
	global_store_dwordx2 v115, v[96:97], s[2:3] offset:1024
	global_store_dwordx2 v115, v[98:99], s[2:3] offset:1536
	s_add_u32 s2, s2, 0x400000
	s_addc_u32 s3, s3, 0
	s_add_u32 s0, s0, 0x800000
	s_addc_u32 s1, s1, 0
	global_load_dwordx4 v[18:21], v114, s[0:1] offset:0
	global_load_dwordx4 v[22:25], v114, s[0:1] offset:1024
	global_load_dwordx4 v[26:29], v114, s[0:1] offset:2048
	global_load_dwordx4 v[30:33], v114, s[0:1] offset:3072
	s_waitcnt vmcnt(8)
; __device__ __forceinline__ void phase_ln(float* R, const float* __restrict__ g, const float* __restrict__ b, bf16_t* xbf, float samp_scale, const float* __restrict__ part, int nsplit, bool f32_all) {
;     ...
;   for (int r = gw; r < MT; r += nw) {
;     float* row = R + (size_t)r * 1024;
;     f32x4 v[4];
; #pragma unroll
;     for (int i = 0; i < 4; ++i) v[i] = *(const f32x4*)(row + i * 256 + lane * 4);
;     if (r >= MP) {
;       for (int sp = 0; sp < nsplit; ++sp) {
;         const float* prow = part + ((size_t)sp * MS + (r - MP)) * 1024;
; #pragma unroll
;         for (int i = 0; i < 4; ++i) v[i] = v[i] + *(const f32x4*)(prow + i * 256 + lane * 4);
;       }
;     }
;     float s = 0.f;
; #pragma unroll
;     for (int i = 0; i < 4; ++i) s += v[i][0] + v[i][1] + v[i][2] + v[i][3];
; #pragma unroll
;     for (int o = 32; o >= 1; o >>= 1) s += __shfl_xor(s, o);
;     const float mean = s * (1.f / 1024.f);
;     float ss = 0.f;
; #pragma unroll
;     for (int i = 0; i < 4; ++i) { v[i] = v[i] - mean; ss += v[i][0] * v[i][0] + v[i][1] * v[i][1] + v[i][2] * v[i][2] + v[i][3] * v[i][3]; }
; #pragma unroll
;     for (int o = 32; o >= 1; o >>= 1) ss += __shfl_xor(ss, o);
;     const float rstd = rsqrtf(ss * (1.f / 1024.f) + LN_EPS);
; #pragma unroll
;     for (int i = 0; i < 4; ++i) {
;       const f32x4 y = v[i] * rstd * gv[i] + bv[i];
;       if (r >= MP) *(f32x4*)(row + i * 256 + lane * 4) = y * samp_scale;
;       else if (f32_all) *(f32x4*)(row + i * 256 + lane * 4) = y;
;       if (xbf) {
;         u32x2 wv;
;         wv[0] = cvt_pk_bf16(y[0], y[1]); wv[1] = cvt_pk_bf16(y[2], y[3]);
;         *(u32x2*)(xbf + (size_t)r * 1024 + i * 256 + lane * 4) = wv;
;       }
;     }
	v_pk_add_f32 v[66:67], v[0:1], v[2:3]
	v_pk_add_f32 v[68:69], v[4:5], v[6:7]
	v_pk_add_f32 v[70:71], v[8:9], v[10:11]
	v_pk_add_f32 v[72:73], v[12:13], v[14:15]
	v_pk_add_f32 v[66:67], v[66:67], v[68:69]
	v_pk_add_f32 v[70:71], v[70:71], v[72:73]
	v_pk_add_f32 v[66:67], v[66:67], v[70:71]
	v_add_f32_e32 v66, v66, v67
	s_nop 1
	v_add_f32_dpp v66, v66, v66 row_shr:1 row_mask:0xf bank_mask:0xf bound_ctrl:1
	s_nop 1
	v_add_f32_dpp v66, v66, v66 row_shr:2 row_mask:0xf bank_mask:0xf bound_ctrl:1
	s_nop 1
	v_add_f32_dpp v66, v66, v66 row_shr:4 row_mask:0xf bank_mask:0xf bound_ctrl:1
	s_nop 1
	v_add_f32_dpp v66, v66, v66 row_shr:8 row_mask:0xf bank_mask:0xf bound_ctrl:1
	s_nop 0
	v_readlane_b32 s9, v66, 15
	v_readlane_b32 s10, v66, 31
	v_readlane_b32 s11, v66, 47
	v_readlane_b32 vcc_lo, v66, 63
	s_nop 1
	v_mov_b32_e32 v66, s9
	v_add_f32_e32 v66, s10, v66
	v_add_f32_e32 v66, s11, v66
	v_add_f32_e32 v66, vcc_lo, v66
	v_mul_f32_e32 v116, 0x3a800000, v66
	v_mov_b32_e32 v117, v116
	v_pk_add_f32 v[0:1], v[0:1], v[116:117] neg_lo:[0,1] neg_hi:[0,1]
	v_pk_add_f32 v[2:3], v[2:3], v[116:117] neg_lo:[0,1] neg_hi:[0,1]
	v_pk_add_f32 v[4:5], v[4:5], v[116:117] neg_lo:[0,1] neg_hi:[0,1]
	v_pk_add_f32 v[6:7], v[6:7], v[116:117] neg_lo:[0,1] neg_hi:[0,1]
	v_pk_add_f32 v[8:9], v[8:9], v[116:117] neg_lo:[0,1] neg_hi:[0,1]
	v_pk_add_f32 v[10:11], v[10:11], v[116:117] neg_lo:[0,1] neg_hi:[0,1]
	v_pk_add_f32 v[12:13], v[12:13], v[116:117] neg_lo:[0,1] neg_hi:[0,1]
	v_pk_add_f32 v[14:15], v[14:15], v[116:117] neg_lo:[0,1] neg_hi:[0,1]
	v_pk_mul_f32 v[66:67], v[0:1], v[0:1]
	v_pk_mul_f32 v[68:69], v[2:3], v[2:3]
	v_pk_fma_f32 v[66:67], v[4:5], v[4:5], v[66:67]
	v_pk_fma_f32 v[68:69], v[6:7], v[6:7], v[68:69]
	v_pk_fma_f32 v[66:67], v[8:9], v[8:9], v[66:67]
	v_pk_fma_f32 v[68:69], v[10:11], v[10:11], v[68:69]
	v_pk_fma_f32 v[66:67], v[12:13], v[12:13], v[66:67]
	v_pk_fma_f32 v[68:69], v[14:15], v[14:15], v[68:69]
	v_pk_add_f32 v[66:67], v[66:67], v[68:69]
	v_add_f32_e32 v66, v66, v67
	s_nop 1
	v_add_f32_dpp v66, v66, v66 row_shr:1 row_mask:0xf bank_mask:0xf bound_ctrl:1
	s_nop 1
	v_add_f32_dpp v66, v66, v66 row_shr:2 row_mask:0xf bank_mask:0xf bound_ctrl:1
	s_nop 1
	v_add_f32_dpp v66, v66, v66 row_shr:4 row_mask:0xf bank_mask:0xf bound_ctrl:1
	s_nop 1
	v_add_f32_dpp v66, v66, v66 row_shr:8 row_mask:0xf bank_mask:0xf bound_ctrl:1
	s_nop 0
	v_readlane_b32 s9, v66, 15
	v_readlane_b32 s10, v66, 31
	v_readlane_b32 s11, v66, 47
	v_readlane_b32 vcc_lo, v66, 63
	s_nop 1
	v_mov_b32_e32 v66, s9
	v_add_f32_e32 v66, s10, v66
	v_add_f32_e32 v66, s11, v66
	v_add_f32_e32 v66, vcc_lo, v66
	v_mul_f32_e32 v66, 0x3a800000, v66
	v_add_f32_e32 v66, 0x3727c5ac, v66
	v_rsq_f32_e32 v118, v66
	s_nop 0
	v_mov_b32_e32 v119, v118
	v_pk_mul_f32 v[0:1], v[0:1], v[118:119]
	v_pk_mul_f32 v[2:3], v[2:3], v[118:119]
	v_pk_mul_f32 v[4:5], v[4:5], v[118:119]
	v_pk_mul_f32 v[6:7], v[6:7], v[118:119]
	v_pk_mul_f32 v[8:9], v[8:9], v[118:119]
	v_pk_mul_f32 v[10:11], v[10:11], v[118:119]
	v_pk_mul_f32 v[12:13], v[12:13], v[118:119]
	v_pk_mul_f32 v[14:15], v[14:15], v[118:119]
	v_pk_fma_f32 v[76:77], v[0:1], v[34:35], v[50:51]
	v_pk_fma_f32 v[78:79], v[2:3], v[36:37], v[52:53]
	v_pk_fma_f32 v[80:81], v[4:5], v[38:39], v[54:55]
	v_pk_fma_f32 v[82:83], v[6:7], v[40:41], v[56:57]
	v_pk_fma_f32 v[84:85], v[8:9], v[42:43], v[58:59]
	v_pk_fma_f32 v[86:87], v[10:11], v[44:45], v[60:61]
	v_pk_fma_f32 v[88:89], v[12:13], v[46:47], v[62:63]
	v_pk_fma_f32 v[90:91], v[14:15], v[48:49], v[64:65]
	v_cvt_pk_bf16_f32 v92, v76, v77
	v_cvt_pk_bf16_f32 v93, v78, v79
	v_cvt_pk_bf16_f32 v94, v80, v81
	v_cvt_pk_bf16_f32 v95, v82, v83
	v_cvt_pk_bf16_f32 v96, v84, v85
	v_cvt_pk_bf16_f32 v97, v86, v87
	v_cvt_pk_bf16_f32 v98, v88, v89
	v_cvt_pk_bf16_f32 v99, v90, v91
	global_store_dwordx2 v115, v[92:93], s[2:3] offset:0
	global_store_dwordx2 v115, v[94:95], s[2:3] offset:512
	global_store_dwordx2 v115, v[96:97], s[2:3] offset:1024
	global_store_dwordx2 v115, v[98:99], s[2:3] offset:1536
	s_add_u32 s2, s2, 0x400000
	s_addc_u32 s3, s3, 0
	s_add_u32 s0, s0, 0x800000
	s_addc_u32 s1, s1, 0
	global_load_dwordx4 v[0:3], v114, s[0:1] offset:0
	global_load_dwordx4 v[4:7], v114, s[0:1] offset:1024
	global_load_dwordx4 v[8:11], v114, s[0:1] offset:2048
	global_load_dwordx4 v[12:15], v114, s[0:1] offset:3072
	s_waitcnt vmcnt(8)
; __device__ __forceinline__ void phase_ln(float* R, const float* __restrict__ g, const float* __restrict__ b, bf16_t* xbf, float samp_scale, const float* __restrict__ part, int nsplit, bool f32_all) {
;     ...
;   for (int r = gw; r < MT; r += nw) {
;     float* row = R + (size_t)r * 1024;
;     f32x4 v[4];
; #pragma unroll
;     for (int i = 0; i < 4; ++i) v[i] = *(const f32x4*)(row + i * 256 + lane * 4);
;     if (r >= MP) {
;       for (int sp = 0; sp < nsplit; ++sp) {
;         const float* prow = part + ((size_t)sp * MS + (r - MP)) * 1024;
; #pragma unroll
;         for (int i = 0; i < 4; ++i) v[i] = v[i] + *(const f32x4*)(prow + i * 256 + lane * 4);
;       }
;     }
;     float s = 0.f;
; #pragma unroll
;     for (int i = 0; i < 4; ++i) s += v[i][0] + v[i][1] + v[i][2] + v[i][3];
; #pragma unroll
;     for (int o = 32; o >= 1; o >>= 1) s += __shfl_xor(s, o);
;     const float mean = s * (1.f / 1024.f);
;     float ss = 0.f;
; #pragma unroll
;     for (int i = 0; i < 4; ++i) { v[i] = v[i] - mean; ss += v[i][0] * v[i][0] + v[i][1] * v[i][1] + v[i][2] * v[i][2] + v[i][3] * v[i][3]; }
; #pragma unroll
;     for (int o = 32; o >= 1; o >>= 1) ss += __shfl_xor(ss, o);
;     const float rstd = rsqrtf(ss * (1.f / 1024.f) + LN_EPS);
; #pragma unroll
;     for (int i = 0; i < 4; ++i) {
;       const f32x4 y = v[i] * rstd * gv[i] + bv[i];
;       if (r >= MP) *(f32x4*)(row + i * 256 + lane * 4) = y * samp_scale;
;       else if (f32_all) *(f32x4*)(row + i * 256 + lane * 4) = y;
;       if (xbf) {
;         u32x2 wv;
;         wv[0] = cvt_pk_bf16(y[0], y[1]); wv[1] = cvt_pk_bf16(y[2], y[3]);
;         *(u32x2*)(xbf + (size_t)r * 1024 + i * 256 + lane * 4) = wv;
;       }
;     }
	v_pk_add_f32 v[66:67], v[18:19], v[20:21]
	v_pk_add_f32 v[68:69], v[22:23], v[24:25]
	v_pk_add_f32 v[70:71], v[26:27], v[28:29]
	v_pk_add_f32 v[72:73], v[30:31], v[32:33]
	v_pk_add_f32 v[66:67], v[66:67], v[68:69]
	v_pk_add_f32 v[70:71], v[70:71], v[72:73]
	v_pk_add_f32 v[66:67], v[66:67], v[70:71]
	v_add_f32_e32 v66, v66, v67
	s_nop 1
	v_add_f32_dpp v66, v66, v66 row_shr:1 row_mask:0xf bank_mask:0xf bound_ctrl:1
	s_nop 1
	v_add_f32_dpp v66, v66, v66 row_shr:2 row_mask:0xf bank_mask:0xf bound_ctrl:1
	s_nop 1
	v_add_f32_dpp v66, v66, v66 row_shr:4 row_mask:0xf bank_mask:0xf bound_ctrl:1
	s_nop 1
	v_add_f32_dpp v66, v66, v66 row_shr:8 row_mask:0xf bank_mask:0xf bound_ctrl:1
	s_nop 0
	v_readlane_b32 s9, v66, 15
	v_readlane_b32 s10, v66, 31
	v_readlane_b32 s11, v66, 47
	v_readlane_b32 vcc_lo, v66, 63
	s_nop 1
	v_mov_b32_e32 v66, s9
	v_add_f32_e32 v66, s10, v66
	v_add_f32_e32 v66, s11, v66
	v_add_f32_e32 v66, vcc_lo, v66
	v_mul_f32_e32 v116, 0x3a800000, v66
	v_mov_b32_e32 v117, v116
	v_pk_add_f32 v[18:19], v[18:19], v[116:117] neg_lo:[0,1] neg_hi:[0,1]
	v_pk_add_f32 v[20:21], v[20:21], v[116:117] neg_lo:[0,1] neg_hi:[0,1]
	v_pk_add_f32 v[22:23], v[22:23], v[116:117] neg_lo:[0,1] neg_hi:[0,1]
	v_pk_add_f32 v[24:25], v[24:25], v[116:117] neg_lo:[0,1] neg_hi:[0,1]
	v_pk_add_f32 v[26:27], v[26:27], v[116:117] neg_lo:[0,1] neg_hi:[0,1]
	v_pk_add_f32 v[28:29], v[28:29], v[116:117] neg_lo:[0,1] neg_hi:[0,1]
	v_pk_add_f32 v[30:31], v[30:31], v[116:117] neg_lo:[0,1] neg_hi:[0,1]
	v_pk_add_f32 v[32:33], v[32:33], v[116:117] neg_lo:[0,1] neg_hi:[0,1]
	v_pk_mul_f32 v[66:67], v[18:19], v[18:19]
	v_pk_mul_f32 v[68:69], v[20:21], v[20:21]
	v_pk_fma_f32 v[66:67], v[22:23], v[22:23], v[66:67]
	v_pk_fma_f32 v[68:69], v[24:25], v[24:25], v[68:69]
	v_pk_fma_f32 v[66:67], v[26:27], v[26:27], v[66:67]
	v_pk_fma_f32 v[68:69], v[28:29], v[28:29], v[68:69]
	v_pk_fma_f32 v[66:67], v[30:31], v[30:31], v[66:67]
	v_pk_fma_f32 v[68:69], v[32:33], v[32:33], v[68:69]
	v_pk_add_f32 v[66:67], v[66:67], v[68:69]
	v_add_f32_e32 v66, v66, v67
	s_nop 1
	v_add_f32_dpp v66, v66, v66 row_shr:1 row_mask:0xf bank_mask:0xf bound_ctrl:1
	s_nop 1
	v_add_f32_dpp v66, v66, v66 row_shr:2 row_mask:0xf bank_mask:0xf bound_ctrl:1
	s_nop 1
	v_add_f32_dpp v66, v66, v66 row_shr:4 row_mask:0xf bank_mask:0xf bound_ctrl:1
	s_nop 1
	v_add_f32_dpp v66, v66, v66 row_shr:8 row_mask:0xf bank_mask:0xf bound_ctrl:1
	s_nop 0
	v_readlane_b32 s9, v66, 15
	v_readlane_b32 s10, v66, 31
	v_readlane_b32 s11, v66, 47
	v_readlane_b32 vcc_lo, v66, 63
	s_nop 1
	v_mov_b32_e32 v66, s9
	v_add_f32_e32 v66, s10, v66
	v_add_f32_e32 v66, s11, v66
	v_add_f32_e32 v66, vcc_lo, v66
	v_mul_f32_e32 v66, 0x3a800000, v66
	v_add_f32_e32 v66, 0x3727c5ac, v66
	v_rsq_f32_e32 v118, v66
	s_nop 0
	v_mov_b32_e32 v119, v118
	v_pk_mul_f32 v[18:19], v[18:19], v[118:119]
	v_pk_mul_f32 v[20:21], v[20:21], v[118:119]
	v_pk_mul_f32 v[22:23], v[22:23], v[118:119]
	v_pk_mul_f32 v[24:25], v[24:25], v[118:119]
	v_pk_mul_f32 v[26:27], v[26:27], v[118:119]
	v_pk_mul_f32 v[28:29], v[28:29], v[118:119]
	v_pk_mul_f32 v[30:31], v[30:31], v[118:119]
	v_pk_mul_f32 v[32:33], v[32:33], v[118:119]
	v_pk_fma_f32 v[76:77], v[18:19], v[34:35], v[50:51]
	v_pk_fma_f32 v[78:79], v[20:21], v[36:37], v[52:53]
	v_pk_fma_f32 v[80:81], v[22:23], v[38:39], v[54:55]
	v_pk_fma_f32 v[82:83], v[24:25], v[40:41], v[56:57]
	v_pk_fma_f32 v[84:85], v[26:27], v[42:43], v[58:59]
	v_pk_fma_f32 v[86:87], v[28:29], v[44:45], v[60:61]
	v_pk_fma_f32 v[88:89], v[30:31], v[46:47], v[62:63]
	v_pk_fma_f32 v[90:91], v[32:33], v[48:49], v[64:65]
	v_cvt_pk_bf16_f32 v92, v76, v77
	v_cvt_pk_bf16_f32 v93, v78, v79
	v_cvt_pk_bf16_f32 v94, v80, v81
	v_cvt_pk_bf16_f32 v95, v82, v83
	v_cvt_pk_bf16_f32 v96, v84, v85
	v_cvt_pk_bf16_f32 v97, v86, v87
	v_cvt_pk_bf16_f32 v98, v88, v89
	v_cvt_pk_bf16_f32 v99, v90, v91
	global_store_dwordx2 v115, v[92:93], s[2:3] offset:0
	global_store_dwordx2 v115, v[94:95], s[2:3] offset:512
	global_store_dwordx2 v115, v[96:97], s[2:3] offset:1024
	global_store_dwordx2 v115, v[98:99], s[2:3] offset:1536
	s_add_u32 s2, s2, 0x400000
	s_addc_u32 s3, s3, 0
	s_add_u32 s0, s0, 0x800000
	s_addc_u32 s1, s1, 0
	global_load_dwordx4 v[18:21], v114, s[0:1] offset:0
	global_load_dwordx4 v[22:25], v114, s[0:1] offset:1024
	global_load_dwordx4 v[26:29], v114, s[0:1] offset:2048
	global_load_dwordx4 v[30:33], v114, s[0:1] offset:3072
	s_waitcnt vmcnt(8)
; __device__ __forceinline__ void phase_ln(float* R, const float* __restrict__ g, const float* __restrict__ b, bf16_t* xbf, float samp_scale, const float* __restrict__ part, int nsplit, bool f32_all) {
;     ...
;   for (int r = gw; r < MT; r += nw) {
;     float* row = R + (size_t)r * 1024;
;     f32x4 v[4];
; #pragma unroll
;     for (int i = 0; i < 4; ++i) v[i] = *(const f32x4*)(row + i * 256 + lane * 4);
;     if (r >= MP) {
;       for (int sp = 0; sp < nsplit; ++sp) {
;         const float* prow = part + ((size_t)sp * MS + (r - MP)) * 1024;
; #pragma unroll
;         for (int i = 0; i < 4; ++i) v[i] = v[i] + *(const f32x4*)(prow + i * 256 + lane * 4);
;       }
;     }
;     float s = 0.f;
; #pragma unroll
;     for (int i = 0; i < 4; ++i) s += v[i][0] + v[i][1] + v[i][2] + v[i][3];
; #pragma unroll
;     for (int o = 32; o >= 1; o >>= 1) s += __shfl_xor(s, o);
;     const float mean = s * (1.f / 1024.f);
;     float ss = 0.f;
; #pragma unroll
;     for (int i = 0; i < 4; ++i) { v[i] = v[i] - mean; ss += v[i][0] * v[i][0] + v[i][1] * v[i][1] + v[i][2] * v[i][2] + v[i][3] * v[i][3]; }
; #pragma unroll
;     for (int o = 32; o >= 1; o >>= 1) ss += __shfl_xor(ss, o);
;     const float rstd = rsqrtf(ss * (1.f / 1024.f) + LN_EPS);
; #pragma unroll
;     for (int i = 0; i < 4; ++i) {
;       const f32x4 y = v[i] * rstd * gv[i] + bv[i];
;       if (r >= MP) *(f32x4*)(row + i * 256 + lane * 4) = y * samp_scale;
;       else if (f32_all) *(f32x4*)(row + i * 256 + lane * 4) = y;
;       if (xbf) {
;         u32x2 wv;
;         wv[0] = cvt_pk_bf16(y[0], y[1]); wv[1] = cvt_pk_bf16(y[2], y[3]);
;         *(u32x2*)(xbf + (size_t)r * 1024 + i * 256 + lane * 4) = wv;
;       }
;     }
	v_pk_add_f32 v[66:67], v[0:1], v[2:3]
	v_pk_add_f32 v[68:69], v[4:5], v[6:7]
	v_pk_add_f32 v[70:71], v[8:9], v[10:11]
	v_pk_add_f32 v[72:73], v[12:13], v[14:15]
	v_pk_add_f32 v[66:67], v[66:67], v[68:69]
	v_pk_add_f32 v[70:71], v[70:71], v[72:73]
	v_pk_add_f32 v[66:67], v[66:67], v[70:71]
	v_add_f32_e32 v66, v66, v67
	s_nop 1
	v_add_f32_dpp v66, v66, v66 row_shr:1 row_mask:0xf bank_mask:0xf bound_ctrl:1
	s_nop 1
	v_add_f32_dpp v66, v66, v66 row_shr:2 row_mask:0xf bank_mask:0xf bound_ctrl:1
	s_nop 1
	v_add_f32_dpp v66, v66, v66 row_shr:4 row_mask:0xf bank_mask:0xf bound_ctrl:1
	s_nop 1
	v_add_f32_dpp v66, v66, v66 row_shr:8 row_mask:0xf bank_mask:0xf bound_ctrl:1
	s_nop 0
	v_readlane_b32 s9, v66, 15
	v_readlane_b32 s10, v66, 31
	v_readlane_b32 s11, v66, 47
	v_readlane_b32 vcc_lo, v66, 63
	s_nop 1
	v_mov_b32_e32 v66, s9
	v_add_f32_e32 v66, s10, v66
	v_add_f32_e32 v66, s11, v66
	v_add_f32_e32 v66, vcc_lo, v66
	v_mul_f32_e32 v116, 0x3a800000, v66
	v_mov_b32_e32 v117, v116
	v_pk_add_f32 v[0:1], v[0:1], v[116:117] neg_lo:[0,1] neg_hi:[0,1]
	v_pk_add_f32 v[2:3], v[2:3], v[116:117] neg_lo:[0,1] neg_hi:[0,1]
	v_pk_add_f32 v[4:5], v[4:5], v[116:117] neg_lo:[0,1] neg_hi:[0,1]
	v_pk_add_f32 v[6:7], v[6:7], v[116:117] neg_lo:[0,1] neg_hi:[0,1]
	v_pk_add_f32 v[8:9], v[8:9], v[116:117] neg_lo:[0,1] neg_hi:[0,1]
	v_pk_add_f32 v[10:11], v[10:11], v[116:117] neg_lo:[0,1] neg_hi:[0,1]
	v_pk_add_f32 v[12:13], v[12:13], v[116:117] neg_lo:[0,1] neg_hi:[0,1]
	v_pk_add_f32 v[14:15], v[14:15], v[116:117] neg_lo:[0,1] neg_hi:[0,1]
	v_pk_mul_f32 v[66:67], v[0:1], v[0:1]
	v_pk_mul_f32 v[68:69], v[2:3], v[2:3]
	v_pk_fma_f32 v[66:67], v[4:5], v[4:5], v[66:67]
	v_pk_fma_f32 v[68:69], v[6:7], v[6:7], v[68:69]
	v_pk_fma_f32 v[66:67], v[8:9], v[8:9], v[66:67]
	v_pk_fma_f32 v[68:69], v[10:11], v[10:11], v[68:69]
	v_pk_fma_f32 v[66:67], v[12:13], v[12:13], v[66:67]
	v_pk_fma_f32 v[68:69], v[14:15], v[14:15], v[68:69]
	v_pk_add_f32 v[66:67], v[66:67], v[68:69]
	v_add_f32_e32 v66, v66, v67
	s_nop 1
	v_add_f32_dpp v66, v66, v66 row_shr:1 row_mask:0xf bank_mask:0xf bound_ctrl:1
	s_nop 1
	v_add_f32_dpp v66, v66, v66 row_shr:2 row_mask:0xf bank_mask:0xf bound_ctrl:1
	s_nop 1
	v_add_f32_dpp v66, v66, v66 row_shr:4 row_mask:0xf bank_mask:0xf bound_ctrl:1
	s_nop 1
	v_add_f32_dpp v66, v66, v66 row_shr:8 row_mask:0xf bank_mask:0xf bound_ctrl:1
	s_nop 0
	v_readlane_b32 s9, v66, 15
	v_readlane_b32 s10, v66, 31
	v_readlane_b32 s11, v66, 47
	v_readlane_b32 vcc_lo, v66, 63
	s_nop 1
	v_mov_b32_e32 v66, s9
	v_add_f32_e32 v66, s10, v66
	v_add_f32_e32 v66, s11, v66
	v_add_f32_e32 v66, vcc_lo, v66
	v_mul_f32_e32 v66, 0x3a800000, v66
	v_add_f32_e32 v66, 0x3727c5ac, v66
	v_rsq_f32_e32 v118, v66
	s_nop 0
	v_mov_b32_e32 v119, v118
	v_pk_mul_f32 v[0:1], v[0:1], v[118:119]
	v_pk_mul_f32 v[2:3], v[2:3], v[118:119]
	v_pk_mul_f32 v[4:5], v[4:5], v[118:119]
	v_pk_mul_f32 v[6:7], v[6:7], v[118:119]
	v_pk_mul_f32 v[8:9], v[8:9], v[118:119]
	v_pk_mul_f32 v[10:11], v[10:11], v[118:119]
	v_pk_mul_f32 v[12:13], v[12:13], v[118:119]
	v_pk_mul_f32 v[14:15], v[14:15], v[118:119]
	v_pk_fma_f32 v[76:77], v[0:1], v[34:35], v[50:51]
	v_pk_fma_f32 v[78:79], v[2:3], v[36:37], v[52:53]
	v_pk_fma_f32 v[80:81], v[4:5], v[38:39], v[54:55]
	v_pk_fma_f32 v[82:83], v[6:7], v[40:41], v[56:57]
	v_pk_fma_f32 v[84:85], v[8:9], v[42:43], v[58:59]
	v_pk_fma_f32 v[86:87], v[10:11], v[44:45], v[60:61]
	v_pk_fma_f32 v[88:89], v[12:13], v[46:47], v[62:63]
	v_pk_fma_f32 v[90:91], v[14:15], v[48:49], v[64:65]
	v_cvt_pk_bf16_f32 v92, v76, v77
	v_cvt_pk_bf16_f32 v93, v78, v79
	v_cvt_pk_bf16_f32 v94, v80, v81
	v_cvt_pk_bf16_f32 v95, v82, v83
	v_cvt_pk_bf16_f32 v96, v84, v85
	v_cvt_pk_bf16_f32 v97, v86, v87
	v_cvt_pk_bf16_f32 v98, v88, v89
	v_cvt_pk_bf16_f32 v99, v90, v91
	global_store_dwordx2 v115, v[92:93], s[2:3] offset:0
	global_store_dwordx2 v115, v[94:95], s[2:3] offset:512
	global_store_dwordx2 v115, v[96:97], s[2:3] offset:1024
	global_store_dwordx2 v115, v[98:99], s[2:3] offset:1536
	s_add_u32 s2, s2, 0x400000
	s_addc_u32 s3, s3, 0
	s_add_u32 s0, s0, 0x800000
	s_addc_u32 s1, s1, 0
	global_load_dwordx4 v[0:3], v114, s[0:1] offset:0
	global_load_dwordx4 v[4:7], v114, s[0:1] offset:1024
	global_load_dwordx4 v[8:11], v114, s[0:1] offset:2048
	global_load_dwordx4 v[12:15], v114, s[0:1] offset:3072
	s_waitcnt vmcnt(8)
; __device__ __forceinline__ void phase_ln(float* R, const float* __restrict__ g, const float* __restrict__ b, bf16_t* xbf, float samp_scale, const float* __restrict__ part, int nsplit, bool f32_all) {
;     ...
;   for (int r = gw; r < MT; r += nw) {
;     float* row = R + (size_t)r * 1024;
;     f32x4 v[4];
; #pragma unroll
;     for (int i = 0; i < 4; ++i) v[i] = *(const f32x4*)(row + i * 256 + lane * 4);
;     if (r >= MP) {
;       for (int sp = 0; sp < nsplit; ++sp) {
;         const float* prow = part + ((size_t)sp * MS + (r - MP)) * 1024;
; #pragma unroll
;         for (int i = 0; i < 4; ++i) v[i] = v[i] + *(const f32x4*)(prow + i * 256 + lane * 4);
;       }
;     }
;     float s = 0.f;
; #pragma unroll
;     for (int i = 0; i < 4; ++i) s += v[i][0] + v[i][1] + v[i][2] + v[i][3];
; #pragma unroll
;     for (int o = 32; o >= 1; o >>= 1) s += __shfl_xor(s, o);
;     const float mean = s * (1.f / 1024.f);
;     float ss = 0.f;
; #pragma unroll
;     for (int i = 0; i < 4; ++i) { v[i] = v[i] - mean; ss += v[i][0] * v[i][0] + v[i][1] * v[i][1] + v[i][2] * v[i][2] + v[i][3] * v[i][3]; }
; #pragma unroll
;     for (int o = 32; o >= 1; o >>= 1) ss += __shfl_xor(ss, o);
;     const float rstd = rsqrtf(ss * (1.f / 1024.f) + LN_EPS);
; #pragma unroll
;     for (int i = 0; i < 4; ++i) {
;       const f32x4 y = v[i] * rstd * gv[i] + bv[i];
;       if (r >= MP) *(f32x4*)(row + i * 256 + lane * 4) = y * samp_scale;
;       else if (f32_all) *(f32x4*)(row + i * 256 + lane * 4) = y;
;       if (xbf) {
;         u32x2 wv;
;         wv[0] = cvt_pk_bf16(y[0], y[1]); wv[1] = cvt_pk_bf16(y[2], y[3]);
;         *(u32x2*)(xbf + (size_t)r * 1024 + i * 256 + lane * 4) = wv;
;       }
;     }
	v_pk_add_f32 v[66:67], v[18:19], v[20:21]
	v_pk_add_f32 v[68:69], v[22:23], v[24:25]
	v_pk_add_f32 v[70:71], v[26:27], v[28:29]
	v_pk_add_f32 v[72:73], v[30:31], v[32:33]
	v_pk_add_f32 v[66:67], v[66:67], v[68:69]
	v_pk_add_f32 v[70:71], v[70:71], v[72:73]
	v_pk_add_f32 v[66:67], v[66:67], v[70:71]
	v_add_f32_e32 v66, v66, v67
	s_nop 1
	v_add_f32_dpp v66, v66, v66 row_shr:1 row_mask:0xf bank_mask:0xf bound_ctrl:1
	s_nop 1
	v_add_f32_dpp v66, v66, v66 row_shr:2 row_mask:0xf bank_mask:0xf bound_ctrl:1
	s_nop 1
	v_add_f32_dpp v66, v66, v66 row_shr:4 row_mask:0xf bank_mask:0xf bound_ctrl:1
	s_nop 1
	v_add_f32_dpp v66, v66, v66 row_shr:8 row_mask:0xf bank_mask:0xf bound_ctrl:1
	s_nop 0
	v_readlane_b32 s9, v66, 15
	v_readlane_b32 s10, v66, 31
	v_readlane_b32 s11, v66, 47
	v_readlane_b32 vcc_lo, v66, 63
	s_nop 1
	v_mov_b32_e32 v66, s9
	v_add_f32_e32 v66, s10, v66
	v_add_f32_e32 v66, s11, v66
	v_add_f32_e32 v66, vcc_lo, v66
	v_mul_f32_e32 v116, 0x3a800000, v66
	v_mov_b32_e32 v117, v116
	v_pk_add_f32 v[18:19], v[18:19], v[116:117] neg_lo:[0,1] neg_hi:[0,1]
	v_pk_add_f32 v[20:21], v[20:21], v[116:117] neg_lo:[0,1] neg_hi:[0,1]
	v_pk_add_f32 v[22:23], v[22:23], v[116:117] neg_lo:[0,1] neg_hi:[0,1]
	v_pk_add_f32 v[24:25], v[24:25], v[116:117] neg_lo:[0,1] neg_hi:[0,1]
	v_pk_add_f32 v[26:27], v[26:27], v[116:117] neg_lo:[0,1] neg_hi:[0,1]
	v_pk_add_f32 v[28:29], v[28:29], v[116:117] neg_lo:[0,1] neg_hi:[0,1]
	v_pk_add_f32 v[30:31], v[30:31], v[116:117] neg_lo:[0,1] neg_hi:[0,1]
	v_pk_add_f32 v[32:33], v[32:33], v[116:117] neg_lo:[0,1] neg_hi:[0,1]
	v_pk_mul_f32 v[66:67], v[18:19], v[18:19]
	v_pk_mul_f32 v[68:69], v[20:21], v[20:21]
	v_pk_fma_f32 v[66:67], v[22:23], v[22:23], v[66:67]
	v_pk_fma_f32 v[68:69], v[24:25], v[24:25], v[68:69]
	v_pk_fma_f32 v[66:67], v[26:27], v[26:27], v[66:67]
	v_pk_fma_f32 v[68:69], v[28:29], v[28:29], v[68:69]
	v_pk_fma_f32 v[66:67], v[30:31], v[30:31], v[66:67]
	v_pk_fma_f32 v[68:69], v[32:33], v[32:33], v[68:69]
	v_pk_add_f32 v[66:67], v[66:67], v[68:69]
	v_add_f32_e32 v66, v66, v67
	s_nop 1
	v_add_f32_dpp v66, v66, v66 row_shr:1 row_mask:0xf bank_mask:0xf bound_ctrl:1
	s_nop 1
	v_add_f32_dpp v66, v66, v66 row_shr:2 row_mask:0xf bank_mask:0xf bound_ctrl:1
	s_nop 1
	v_add_f32_dpp v66, v66, v66 row_shr:4 row_mask:0xf bank_mask:0xf bound_ctrl:1
	s_nop 1
	v_add_f32_dpp v66, v66, v66 row_shr:8 row_mask:0xf bank_mask:0xf bound_ctrl:1
	s_nop 0
	v_readlane_b32 s9, v66, 15
	v_readlane_b32 s10, v66, 31
	v_readlane_b32 s11, v66, 47
	v_readlane_b32 vcc_lo, v66, 63
	s_nop 1
	v_mov_b32_e32 v66, s9
	v_add_f32_e32 v66, s10, v66
	v_add_f32_e32 v66, s11, v66
	v_add_f32_e32 v66, vcc_lo, v66
	v_mul_f32_e32 v66, 0x3a800000, v66
	v_add_f32_e32 v66, 0x3727c5ac, v66
	v_rsq_f32_e32 v118, v66
	s_nop 0
	v_mov_b32_e32 v119, v118
	v_pk_mul_f32 v[18:19], v[18:19], v[118:119]
	v_pk_mul_f32 v[20:21], v[20:21], v[118:119]
	v_pk_mul_f32 v[22:23], v[22:23], v[118:119]
	v_pk_mul_f32 v[24:25], v[24:25], v[118:119]
	v_pk_mul_f32 v[26:27], v[26:27], v[118:119]
	v_pk_mul_f32 v[28:29], v[28:29], v[118:119]
	v_pk_mul_f32 v[30:31], v[30:31], v[118:119]
	v_pk_mul_f32 v[32:33], v[32:33], v[118:119]
	v_pk_fma_f32 v[76:77], v[18:19], v[34:35], v[50:51]
	v_pk_fma_f32 v[78:79], v[20:21], v[36:37], v[52:53]
	v_pk_fma_f32 v[80:81], v[22:23], v[38:39], v[54:55]
	v_pk_fma_f32 v[82:83], v[24:25], v[40:41], v[56:57]
	v_pk_fma_f32 v[84:85], v[26:27], v[42:43], v[58:59]
	v_pk_fma_f32 v[86:87], v[28:29], v[44:45], v[60:61]
	v_pk_fma_f32 v[88:89], v[30:31], v[46:47], v[62:63]
	v_pk_fma_f32 v[90:91], v[32:33], v[48:49], v[64:65]
	v_cvt_pk_bf16_f32 v92, v76, v77
	v_cvt_pk_bf16_f32 v93, v78, v79
	v_cvt_pk_bf16_f32 v94, v80, v81
	v_cvt_pk_bf16_f32 v95, v82, v83
	v_cvt_pk_bf16_f32 v96, v84, v85
	v_cvt_pk_bf16_f32 v97, v86, v87
	v_cvt_pk_bf16_f32 v98, v88, v89
	v_cvt_pk_bf16_f32 v99, v90, v91
	global_store_dwordx2 v115, v[92:93], s[2:3] offset:0
	global_store_dwordx2 v115, v[94:95], s[2:3] offset:512
	global_store_dwordx2 v115, v[96:97], s[2:3] offset:1024
	global_store_dwordx2 v115, v[98:99], s[2:3] offset:1536
	s_add_u32 s2, s2, 0x400000
	s_addc_u32 s3, s3, 0
	s_add_u32 s0, s0, 0x800000
	s_addc_u32 s1, s1, 0
	global_load_dwordx4 v[18:21], v114, s[0:1] offset:0
	global_load_dwordx4 v[22:25], v114, s[0:1] offset:1024
	global_load_dwordx4 v[26:29], v114, s[0:1] offset:2048
	global_load_dwordx4 v[30:33], v114, s[0:1] offset:3072
	s_waitcnt vmcnt(8)
; __device__ __forceinline__ void phase_ln(float* R, const float* __restrict__ g, const float* __restrict__ b, bf16_t* xbf, float samp_scale, const float* __restrict__ part, int nsplit, bool f32_all) {
;     ...
;   for (int r = gw; r < MT; r += nw) {
;     float* row = R + (size_t)r * 1024;
;     f32x4 v[4];
; #pragma unroll
;     for (int i = 0; i < 4; ++i) v[i] = *(const f32x4*)(row + i * 256 + lane * 4);
;     if (r >= MP) {
;       for (int sp = 0; sp < nsplit; ++sp) {
;         const float* prow = part + ((size_t)sp * MS + (r - MP)) * 1024;
; #pragma unroll
;         for (int i = 0; i < 4; ++i) v[i] = v[i] + *(const f32x4*)(prow + i * 256 + lane * 4);
;       }
;     }
;     float s = 0.f;
; #pragma unroll
;     for (int i = 0; i < 4; ++i) s += v[i][0] + v[i][1] + v[i][2] + v[i][3];
; #pragma unroll
;     for (int o = 32; o >= 1; o >>= 1) s += __shfl_xor(s, o);
;     const float mean = s * (1.f / 1024.f);
;     float ss = 0.f;
; #pragma unroll
;     for (int i = 0; i < 4; ++i) { v[i] = v[i] - mean; ss += v[i][0] * v[i][0] + v[i][1] * v[i][1] + v[i][2] * v[i][2] + v[i][3] * v[i][3]; }
; #pragma unroll
;     for (int o = 32; o >= 1; o >>= 1) ss += __shfl_xor(ss, o);
;     const float rstd = rsqrtf(ss * (1.f / 1024.f) + LN_EPS);
; #pragma unroll
;     for (int i = 0; i < 4; ++i) {
;       const f32x4 y = v[i] * rstd * gv[i] + bv[i];
;       if (r >= MP) *(f32x4*)(row + i * 256 + lane * 4) = y * samp_scale;
;       else if (f32_all) *(f32x4*)(row + i * 256 + lane * 4) = y;
;       if (xbf) {
;         u32x2 wv;
;         wv[0] = cvt_pk_bf16(y[0], y[1]); wv[1] = cvt_pk_bf16(y[2], y[3]);
;         *(u32x2*)(xbf + (size_t)r * 1024 + i * 256 + lane * 4) = wv;
;       }
;     }
	v_pk_add_f32 v[66:67], v[0:1], v[2:3]
	v_pk_add_f32 v[68:69], v[4:5], v[6:7]
	v_pk_add_f32 v[70:71], v[8:9], v[10:11]
	v_pk_add_f32 v[72:73], v[12:13], v[14:15]
	v_pk_add_f32 v[66:67], v[66:67], v[68:69]
	v_pk_add_f32 v[70:71], v[70:71], v[72:73]
	v_pk_add_f32 v[66:67], v[66:67], v[70:71]
	v_add_f32_e32 v66, v66, v67
	s_nop 1
	v_add_f32_dpp v66, v66, v66 row_shr:1 row_mask:0xf bank_mask:0xf bound_ctrl:1
	s_nop 1
	v_add_f32_dpp v66, v66, v66 row_shr:2 row_mask:0xf bank_mask:0xf bound_ctrl:1
	s_nop 1
	v_add_f32_dpp v66, v66, v66 row_shr:4 row_mask:0xf bank_mask:0xf bound_ctrl:1
	s_nop 1
	v_add_f32_dpp v66, v66, v66 row_shr:8 row_mask:0xf bank_mask:0xf bound_ctrl:1
	s_nop 0
	v_readlane_b32 s9, v66, 15
	v_readlane_b32 s10, v66, 31
	v_readlane_b32 s11, v66, 47
	v_readlane_b32 vcc_lo, v66, 63
	s_nop 1
	v_mov_b32_e32 v66, s9
	v_add_f32_e32 v66, s10, v66
	v_add_f32_e32 v66, s11, v66
	v_add_f32_e32 v66, vcc_lo, v66
	v_mul_f32_e32 v116, 0x3a800000, v66
	v_mov_b32_e32 v117, v116
	v_pk_add_f32 v[0:1], v[0:1], v[116:117] neg_lo:[0,1] neg_hi:[0,1]
	v_pk_add_f32 v[2:3], v[2:3], v[116:117] neg_lo:[0,1] neg_hi:[0,1]
	v_pk_add_f32 v[4:5], v[4:5], v[116:117] neg_lo:[0,1] neg_hi:[0,1]
	v_pk_add_f32 v[6:7], v[6:7], v[116:117] neg_lo:[0,1] neg_hi:[0,1]
	v_pk_add_f32 v[8:9], v[8:9], v[116:117] neg_lo:[0,1] neg_hi:[0,1]
	v_pk_add_f32 v[10:11], v[10:11], v[116:117] neg_lo:[0,1] neg_hi:[0,1]
	v_pk_add_f32 v[12:13], v[12:13], v[116:117] neg_lo:[0,1] neg_hi:[0,1]
	v_pk_add_f32 v[14:15], v[14:15], v[116:117] neg_lo:[0,1] neg_hi:[0,1]
	v_pk_mul_f32 v[66:67], v[0:1], v[0:1]
	v_pk_mul_f32 v[68:69], v[2:3], v[2:3]
	v_pk_fma_f32 v[66:67], v[4:5], v[4:5], v[66:67]
	v_pk_fma_f32 v[68:69], v[6:7], v[6:7], v[68:69]
	v_pk_fma_f32 v[66:67], v[8:9], v[8:9], v[66:67]
	v_pk_fma_f32 v[68:69], v[10:11], v[10:11], v[68:69]
	v_pk_fma_f32 v[66:67], v[12:13], v[12:13], v[66:67]
	v_pk_fma_f32 v[68:69], v[14:15], v[14:15], v[68:69]
	v_pk_add_f32 v[66:67], v[66:67], v[68:69]
	v_add_f32_e32 v66, v66, v67
	s_nop 1
	v_add_f32_dpp v66, v66, v66 row_shr:1 row_mask:0xf bank_mask:0xf bound_ctrl:1
	s_nop 1
	v_add_f32_dpp v66, v66, v66 row_shr:2 row_mask:0xf bank_mask:0xf bound_ctrl:1
	s_nop 1
	v_add_f32_dpp v66, v66, v66 row_shr:4 row_mask:0xf bank_mask:0xf bound_ctrl:1
	s_nop 1
	v_add_f32_dpp v66, v66, v66 row_shr:8 row_mask:0xf bank_mask:0xf bound_ctrl:1
	s_nop 0
	v_readlane_b32 s9, v66, 15
	v_readlane_b32 s10, v66, 31
	v_readlane_b32 s11, v66, 47
	v_readlane_b32 vcc_lo, v66, 63
	s_nop 1
	v_mov_b32_e32 v66, s9
	v_add_f32_e32 v66, s10, v66
	v_add_f32_e32 v66, s11, v66
	v_add_f32_e32 v66, vcc_lo, v66
	v_mul_f32_e32 v66, 0x3a800000, v66
	v_add_f32_e32 v66, 0x3727c5ac, v66
	v_rsq_f32_e32 v118, v66
	s_nop 0
	v_mov_b32_e32 v119, v118
	v_pk_mul_f32 v[0:1], v[0:1], v[118:119]
	v_pk_mul_f32 v[2:3], v[2:3], v[118:119]
	v_pk_mul_f32 v[4:5], v[4:5], v[118:119]
	v_pk_mul_f32 v[6:7], v[6:7], v[118:119]
	v_pk_mul_f32 v[8:9], v[8:9], v[118:119]
	v_pk_mul_f32 v[10:11], v[10:11], v[118:119]
	v_pk_mul_f32 v[12:13], v[12:13], v[118:119]
	v_pk_mul_f32 v[14:15], v[14:15], v[118:119]
	v_pk_fma_f32 v[76:77], v[0:1], v[34:35], v[50:51]
	v_pk_fma_f32 v[78:79], v[2:3], v[36:37], v[52:53]
	v_pk_fma_f32 v[80:81], v[4:5], v[38:39], v[54:55]
	v_pk_fma_f32 v[82:83], v[6:7], v[40:41], v[56:57]
	v_pk_fma_f32 v[84:85], v[8:9], v[42:43], v[58:59]
	v_pk_fma_f32 v[86:87], v[10:11], v[44:45], v[60:61]
	v_pk_fma_f32 v[88:89], v[12:13], v[46:47], v[62:63]
	v_pk_fma_f32 v[90:91], v[14:15], v[48:49], v[64:65]
	v_cvt_pk_bf16_f32 v92, v76, v77
	v_cvt_pk_bf16_f32 v93, v78, v79
	v_cvt_pk_bf16_f32 v94, v80, v81
	v_cvt_pk_bf16_f32 v95, v82, v83
	v_cvt_pk_bf16_f32 v96, v84, v85
	v_cvt_pk_bf16_f32 v97, v86, v87
	v_cvt_pk_bf16_f32 v98, v88, v89
	v_cvt_pk_bf16_f32 v99, v90, v91
	global_store_dwordx2 v115, v[92:93], s[2:3] offset:0
	global_store_dwordx2 v115, v[94:95], s[2:3] offset:512
	global_store_dwordx2 v115, v[96:97], s[2:3] offset:1024
	global_store_dwordx2 v115, v[98:99], s[2:3] offset:1536
	s_add_u32 s2, s2, 0x400000
	s_addc_u32 s3, s3, 0
	s_waitcnt vmcnt(4)
; __device__ __forceinline__ void phase_ln(float* R, const float* __restrict__ g, const float* __restrict__ b, bf16_t* xbf, float samp_scale, const float* __restrict__ part, int nsplit, bool f32_all) {
;     ...
;   for (int r = gw; r < MT; r += nw) {
;     float* row = R + (size_t)r * 1024;
;     f32x4 v[4];
; #pragma unroll
;     for (int i = 0; i < 4; ++i) v[i] = *(const f32x4*)(row + i * 256 + lane * 4);
;     if (r >= MP) {
;       for (int sp = 0; sp < nsplit; ++sp) {
;         const float* prow = part + ((size_t)sp * MS + (r - MP)) * 1024;
; #pragma unroll
;         for (int i = 0; i < 4; ++i) v[i] = v[i] + *(const f32x4*)(prow + i * 256 + lane * 4);
;       }
;     }
;     float s = 0.f;
; #pragma unroll
;     for (int i = 0; i < 4; ++i) s += v[i][0] + v[i][1] + v[i][2] + v[i][3];
; #pragma unroll
;     for (int o = 32; o >= 1; o >>= 1) s += __shfl_xor(s, o);
;     const float mean = s * (1.f / 1024.f);
;     float ss = 0.f;
; #pragma unroll
;     for (int i = 0; i < 4; ++i) { v[i] = v[i] - mean; ss += v[i][0] * v[i][0] + v[i][1] * v[i][1] + v[i][2] * v[i][2] + v[i][3] * v[i][3]; }
; #pragma unroll
;     for (int o = 32; o >= 1; o >>= 1) ss += __shfl_xor(ss, o);
;     const float rstd = rsqrtf(ss * (1.f / 1024.f) + LN_EPS);
; #pragma unroll
;     for (int i = 0; i < 4; ++i) {
;       const f32x4 y = v[i] * rstd * gv[i] + bv[i];
;       if (r >= MP) *(f32x4*)(row + i * 256 + lane * 4) = y * samp_scale;
;       else if (f32_all) *(f32x4*)(row + i * 256 + lane * 4) = y;
;       if (xbf) {
;         u32x2 wv;
;         wv[0] = cvt_pk_bf16(y[0], y[1]); wv[1] = cvt_pk_bf16(y[2], y[3]);
;         *(u32x2*)(xbf + (size_t)r * 1024 + i * 256 + lane * 4) = wv;
;       }
;     }
;   }
	v_pk_add_f32 v[66:67], v[18:19], v[20:21]
	v_pk_add_f32 v[68:69], v[22:23], v[24:25]
	v_pk_add_f32 v[70:71], v[26:27], v[28:29]
	v_pk_add_f32 v[72:73], v[30:31], v[32:33]
	v_pk_add_f32 v[66:67], v[66:67], v[68:69]
	v_pk_add_f32 v[70:71], v[70:71], v[72:73]
	v_pk_add_f32 v[66:67], v[66:67], v[70:71]
	v_add_f32_e32 v66, v66, v67
	s_nop 1
	v_add_f32_dpp v66, v66, v66 row_shr:1 row_mask:0xf bank_mask:0xf bound_ctrl:1
	s_nop 1
	v_add_f32_dpp v66, v66, v66 row_shr:2 row_mask:0xf bank_mask:0xf bound_ctrl:1
	s_nop 1
	v_add_f32_dpp v66, v66, v66 row_shr:4 row_mask:0xf bank_mask:0xf bound_ctrl:1
	s_nop 1
	v_add_f32_dpp v66, v66, v66 row_shr:8 row_mask:0xf bank_mask:0xf bound_ctrl:1
	s_nop 0
	v_readlane_b32 s9, v66, 15
	v_readlane_b32 s10, v66, 31
	v_readlane_b32 s11, v66, 47
	v_readlane_b32 vcc_lo, v66, 63
	s_nop 1
	v_mov_b32_e32 v66, s9
	v_add_f32_e32 v66, s10, v66
	v_add_f32_e32 v66, s11, v66
	v_add_f32_e32 v66, vcc_lo, v66
	v_mul_f32_e32 v116, 0x3a800000, v66
	v_mov_b32_e32 v117, v116
	v_pk_add_f32 v[18:19], v[18:19], v[116:117] neg_lo:[0,1] neg_hi:[0,1]
	v_pk_add_f32 v[20:21], v[20:21], v[116:117] neg_lo:[0,1] neg_hi:[0,1]
	v_pk_add_f32 v[22:23], v[22:23], v[116:117] neg_lo:[0,1] neg_hi:[0,1]
	v_pk_add_f32 v[24:25], v[24:25], v[116:117] neg_lo:[0,1] neg_hi:[0,1]
	v_pk_add_f32 v[26:27], v[26:27], v[116:117] neg_lo:[0,1] neg_hi:[0,1]
	v_pk_add_f32 v[28:29], v[28:29], v[116:117] neg_lo:[0,1] neg_hi:[0,1]
	v_pk_add_f32 v[30:31], v[30:31], v[116:117] neg_lo:[0,1] neg_hi:[0,1]
	v_pk_add_f32 v[32:33], v[32:33], v[116:117] neg_lo:[0,1] neg_hi:[0,1]
	v_pk_mul_f32 v[66:67], v[18:19], v[18:19]
	v_pk_mul_f32 v[68:69], v[20:21], v[20:21]
	v_pk_fma_f32 v[66:67], v[22:23], v[22:23], v[66:67]
	v_pk_fma_f32 v[68:69], v[24:25], v[24:25], v[68:69]
	v_pk_fma_f32 v[66:67], v[26:27], v[26:27], v[66:67]
	v_pk_fma_f32 v[68:69], v[28:29], v[28:29], v[68:69]
	v_pk_fma_f32 v[66:67], v[30:31], v[30:31], v[66:67]
	v_pk_fma_f32 v[68:69], v[32:33], v[32:33], v[68:69]
	v_pk_add_f32 v[66:67], v[66:67], v[68:69]
	v_add_f32_e32 v66, v66, v67
	s_nop 1
	v_add_f32_dpp v66, v66, v66 row_shr:1 row_mask:0xf bank_mask:0xf bound_ctrl:1
	s_nop 1
	v_add_f32_dpp v66, v66, v66 row_shr:2 row_mask:0xf bank_mask:0xf bound_ctrl:1
	s_nop 1
	v_add_f32_dpp v66, v66, v66 row_shr:4 row_mask:0xf bank_mask:0xf bound_ctrl:1
	s_nop 1
	v_add_f32_dpp v66, v66, v66 row_shr:8 row_mask:0xf bank_mask:0xf bound_ctrl:1
	s_nop 0
	v_readlane_b32 s9, v66, 15
	v_readlane_b32 s10, v66, 31
	v_readlane_b32 s11, v66, 47
	v_readlane_b32 vcc_lo, v66, 63
	s_nop 1
	v_mov_b32_e32 v66, s9
	v_add_f32_e32 v66, s10, v66
	v_add_f32_e32 v66, s11, v66
	v_add_f32_e32 v66, vcc_lo, v66
	v_mul_f32_e32 v66, 0x3a800000, v66
	v_add_f32_e32 v66, 0x3727c5ac, v66
	v_rsq_f32_e32 v118, v66
	s_nop 0
	v_mov_b32_e32 v119, v118
	v_pk_mul_f32 v[18:19], v[18:19], v[118:119]
	v_pk_mul_f32 v[20:21], v[20:21], v[118:119]
	v_pk_mul_f32 v[22:23], v[22:23], v[118:119]
	v_pk_mul_f32 v[24:25], v[24:25], v[118:119]
	v_pk_mul_f32 v[26:27], v[26:27], v[118:119]
	v_pk_mul_f32 v[28:29], v[28:29], v[118:119]
	v_pk_mul_f32 v[30:31], v[30:31], v[118:119]
	v_pk_mul_f32 v[32:33], v[32:33], v[118:119]
	v_pk_fma_f32 v[76:77], v[18:19], v[34:35], v[50:51]
	v_pk_fma_f32 v[78:79], v[20:21], v[36:37], v[52:53]
	v_pk_fma_f32 v[80:81], v[22:23], v[38:39], v[54:55]
	v_pk_fma_f32 v[82:83], v[24:25], v[40:41], v[56:57]
	v_pk_fma_f32 v[84:85], v[26:27], v[42:43], v[58:59]
	v_pk_fma_f32 v[86:87], v[28:29], v[44:45], v[60:61]
	v_pk_fma_f32 v[88:89], v[30:31], v[46:47], v[62:63]
	v_pk_fma_f32 v[90:91], v[32:33], v[48:49], v[64:65]
	v_cvt_pk_bf16_f32 v92, v76, v77
	v_cvt_pk_bf16_f32 v93, v78, v79
	v_cvt_pk_bf16_f32 v94, v80, v81
	v_cvt_pk_bf16_f32 v95, v82, v83
	v_cvt_pk_bf16_f32 v96, v84, v85
	v_cvt_pk_bf16_f32 v97, v86, v87
	v_cvt_pk_bf16_f32 v98, v88, v89
	v_cvt_pk_bf16_f32 v99, v90, v91
	global_store_dwordx2 v115, v[92:93], s[2:3] offset:0
	global_store_dwordx2 v115, v[94:95], s[2:3] offset:512
	global_store_dwordx2 v115, v[96:97], s[2:3] offset:1024
	global_store_dwordx2 v115, v[98:99], s[2:3] offset:1536
	s_add_u32 s2, s2, 0x400000
	s_addc_u32 s3, s3, 0
	s_branch .Lln1_end

; __device__ __forceinline__ int otid() { int t = threadIdx.x; asm volatile("" : "+v"(t)); return t; }
; __device__ __forceinline__ void phase_ln(float* R, const float* __restrict__ g, const float* __restrict__ b, bf16_t* xbf, float samp_scale, const float* __restrict__ part, int nsplit, bool f32_all) {
;   const int tid = otid(), lane = tid & 63, gw = blockIdx.x * 8 + (tid >> 6), nw = gridDim.x * 8;
;   f32x4 gv[4], bv[4];
; #pragma unroll
;   for (int i = 0; i < 4; ++i) { gv[i] = *(const f32x4*)(g + i * 256 + lane * 4); bv[i] = *(const f32x4*)(b + i * 256 + lane * 4); }
;   for (int r = gw; r < MT; r += nw) {
;     float* row = R + (size_t)r * 1024;
;     f32x4 v[4];
; #pragma unroll
;     for (int i = 0; i < 4; ++i) v[i] = *(const f32x4*)(row + i * 256 + lane * 4);
;     if (r >= MP) {
;       for (int sp = 0; sp < nsplit; ++sp) {
;         const float* prow = part + ((size_t)sp * MS + (r - MP)) * 1024;
; #pragma unroll
;         for (int i = 0; i < 4; ++i) v[i] = v[i] + *(const f32x4*)(prow + i * 256 + lane * 4);
;       }
;     }
.LBB0_3944:
	s_or_b64 exec, exec, s[0:1]
	v_readlane_b32 s0, v254, 51
	s_nop 0
	s_cmp_lg_u32 s0, 0
	s_cbranch_scc1 .Lln2_orig
	v_readlane_b32 s6, v254, 2
	v_readlane_b32 s7, v254, 3
	v_readlane_b32 s8, v255, 22
	s_waitcnt lgkmcnt(0)
	s_barrier
	s_load_dwordx4 s[0:3], s[6:7], 0x98
	s_load_dwordx4 s[4:7], s[6:7], 0xa8
	v_readlane_b32 s9, v254, 15
	v_readfirstlane_b32 s10, v244
	v_lshlrev_b32_e32 v114, 4, v252
	v_lshlrev_b32_e32 v115, 3, v252
	s_lshr_b32 s10, s10, 6
	s_add_i32 s9, s9, s10
	s_lshl_b32 s11, s8, 12
	s_waitcnt lgkmcnt(0)
	s_add_u32 s0, s0, s11
	s_addc_u32 s1, s1, 0
	s_add_u32 s2, s2, s11
	s_addc_u32 s3, s3, 0
	global_load_dwordx4 v[34:37], v114, s[0:1] offset:0
	global_load_dwordx4 v[38:41], v114, s[0:1] offset:1024
	global_load_dwordx4 v[42:45], v114, s[0:1] offset:2048
	global_load_dwordx4 v[46:49], v114, s[0:1] offset:3072
	global_load_dwordx4 v[50:53], v114, s[2:3] offset:0
	global_load_dwordx4 v[54:57], v114, s[2:3] offset:1024
	global_load_dwordx4 v[58:61], v114, s[2:3] offset:2048
	global_load_dwordx4 v[62:65], v114, s[2:3] offset:3072
	s_lshl_b32 s11, s9, 12
	s_add_u32 s0, s4, s11
	s_addc_u32 s1, s5, 0
	s_lshl_b32 s11, s9, 11
	s_add_u32 s11, s11, 0x39c0000
	s_add_u32 s2, s6, s11
	s_addc_u32 s3, s7, 0
	s_cmp_ge_u32 s10, 2
	s_cbranch_scc1 .Lln2_nosa
	v_readlane_b32 s9, v254, 6
	s_nop 0
	s_lshl_b32 s9, s9, 1
	s_add_i32 s9, s9, s10
	s_lshl_b32 s11, s9, 12
	s_add_u32 s11, s11, 0x1e482000
	s_add_u32 s10, s6, s11
	s_addc_u32 s11, s7, 0
	s_lshl_b32 vcc_lo, s9, 12
	s_add_u32 vcc_lo, vcc_lo, 0x8000000
	s_add_u32 s4, s4, vcc_lo
	s_addc_u32 s5, s5, 0
	s_lshl_b32 vcc_lo, s9, 11
	s_add_u32 vcc_lo, vcc_lo, 0x79c0000
	s_add_u32 s6, s6, vcc_lo
	s_addc_u32 s7, s7, 0
	global_load_dwordx4 v[202:205], v114, s[4:5] offset:0
	global_load_dwordx4 v[206:209], v114, s[4:5] offset:1024
	global_load_dwordx4 v[210:213], v114, s[4:5] offset:2048
	global_load_dwordx4 v[214:217], v114, s[4:5] offset:3072
	global_load_dwordx4 v[122:125], v114, s[10:11] offset:0
	global_load_dwordx4 v[126:129], v114, s[10:11] offset:1024
	global_load_dwordx4 v[130:133], v114, s[10:11] offset:2048
	global_load_dwordx4 v[134:137], v114, s[10:11] offset:3072
	s_add_u32 s10, s10, 0x200000
	s_addc_u32 s11, s11, 0
	global_load_dwordx4 v[138:141], v114, s[10:11] offset:0
	global_load_dwordx4 v[142:145], v114, s[10:11] offset:1024
	global_load_dwordx4 v[146:149], v114, s[10:11] offset:2048
	global_load_dwordx4 v[150:153], v114, s[10:11] offset:3072
	s_add_u32 s10, s10, 0x200000
	s_addc_u32 s11, s11, 0
	global_load_dwordx4 v[154:157], v114, s[10:11] offset:0
	global_load_dwordx4 v[158:161], v114, s[10:11] offset:1024
	global_load_dwordx4 v[162:165], v114, s[10:11] offset:2048
	global_load_dwordx4 v[166:169], v114, s[10:11] offset:3072
	s_add_u32 s10, s10, 0x200000
	s_addc_u32 s11, s11, 0
	global_load_dwordx4 v[170:173], v114, s[10:11] offset:0
	global_load_dwordx4 v[174:177], v114, s[10:11] offset:1024
	global_load_dwordx4 v[178:181], v114, s[10:11] offset:2048
	global_load_dwordx4 v[182:185], v114, s[10:11] offset:3072
	s_add_u32 s10, s10, 0x200000
	s_addc_u32 s11, s11, 0
	global_load_dwordx4 v[186:189], v114, s[10:11] offset:0
	global_load_dwordx4 v[190:193], v114, s[10:11] offset:1024
	global_load_dwordx4 v[194:197], v114, s[10:11] offset:2048
	global_load_dwordx4 v[198:201], v114, s[10:11] offset:3072
	s_add_u32 s10, s10, 0x200000
	s_addc_u32 s11, s11, 0
	global_load_dwordx4 v[18:21], v114, s[10:11] offset:0
	global_load_dwordx4 v[22:25], v114, s[10:11] offset:1024
	global_load_dwordx4 v[26:29], v114, s[10:11] offset:2048
	global_load_dwordx4 v[30:33], v114, s[10:11] offset:3072
	s_add_u32 s10, s10, 0x200000
	s_addc_u32 s11, s11, 0
	global_load_dwordx4 v[66:69], v114, s[10:11] offset:0
	global_load_dwordx4 v[70:73], v114, s[10:11] offset:1024
	global_load_dwordx4 v[74:77], v114, s[10:11] offset:2048
	global_load_dwordx4 v[78:81], v114, s[10:11] offset:3072
	s_add_u32 s10, s10, 0x200000
	s_addc_u32 s11, s11, 0
	global_load_dwordx4 v[82:85], v114, s[10:11] offset:0
	global_load_dwordx4 v[86:89], v114, s[10:11] offset:1024
	global_load_dwordx4 v[90:93], v114, s[10:11] offset:2048
	global_load_dwordx4 v[94:97], v114, s[10:11] offset:3072
.Lln2_nosa:
	global_load_dwordx4 v[0:3], v114, s[0:1] offset:0
	global_load_dwordx4 v[4:7], v114, s[0:1] offset:1024
	global_load_dwordx4 v[8:11], v114, s[0:1] offset:2048
	global_load_dwordx4 v[12:15], v114, s[0:1] offset:3072
	v_readfirstlane_b32 s10, v244
	s_lshr_b32 s10, s10, 6
	s_cmp_ge_u32 s10, 2
	s_cbranch_scc1 .Lln2_nosb
; __device__ __forceinline__ void phase_ln(float* R, const float* __restrict__ g, const float* __restrict__ b, bf16_t* xbf, float samp_scale, const float* __restrict__ part, int nsplit, bool f32_all) {
;     ...
;     if (r >= MP) {
;       for (int sp = 0; sp < nsplit; ++sp) {
;         const float* prow = part + ((size_t)sp * MS + (r - MP)) * 1024;
; #pragma unroll
;         for (int i = 0; i < 4; ++i) v[i] = v[i] + *(const f32x4*)(prow + i * 256 + lane * 4);
;       }
;     }
;     float s = 0.f;
; #pragma unroll
;     for (int i = 0; i < 4; ++i) s += v[i][0] + v[i][1] + v[i][2] + v[i][3];
; #pragma unroll
;     for (int o = 32; o >= 1; o >>= 1) s += __shfl_xor(s, o);
;     const float mean = s * (1.f / 1024.f);
;     float ss = 0.f;
; #pragma unroll
;     for (int i = 0; i < 4; ++i) { v[i] = v[i] - mean; ss += v[i][0] * v[i][0] + v[i][1] * v[i][1] + v[i][2] * v[i][2] + v[i][3] * v[i][3]; }
; #pragma unroll
;     for (int o = 32; o >= 1; o >>= 1) ss += __shfl_xor(ss, o);
;     const float rstd = rsqrtf(ss * (1.f / 1024.f) + LN_EPS);
	s_waitcnt vmcnt(4)
	v_pk_add_f32 v[202:203], v[202:203], v[122:123]
	v_pk_add_f32 v[204:205], v[204:205], v[124:125]
	v_pk_add_f32 v[206:207], v[206:207], v[126:127]
	v_pk_add_f32 v[208:209], v[208:209], v[128:129]
	v_pk_add_f32 v[210:211], v[210:211], v[130:131]
	v_pk_add_f32 v[212:213], v[212:213], v[132:133]
	v_pk_add_f32 v[214:215], v[214:215], v[134:135]
	v_pk_add_f32 v[216:217], v[216:217], v[136:137]
	v_pk_add_f32 v[202:203], v[202:203], v[138:139]
	v_pk_add_f32 v[204:205], v[204:205], v[140:141]
	v_pk_add_f32 v[206:207], v[206:207], v[142:143]
	v_pk_add_f32 v[208:209], v[208:209], v[144:145]
	v_pk_add_f32 v[210:211], v[210:211], v[146:147]
	v_pk_add_f32 v[212:213], v[212:213], v[148:149]
	v_pk_add_f32 v[214:215], v[214:215], v[150:151]
	v_pk_add_f32 v[216:217], v[216:217], v[152:153]
	v_pk_add_f32 v[202:203], v[202:203], v[154:155]
	v_pk_add_f32 v[204:205], v[204:205], v[156:157]
	v_pk_add_f32 v[206:207], v[206:207], v[158:159]
	v_pk_add_f32 v[208:209], v[208:209], v[160:161]
	v_pk_add_f32 v[210:211], v[210:211], v[162:163]
	v_pk_add_f32 v[212:213], v[212:213], v[164:165]
	v_pk_add_f32 v[214:215], v[214:215], v[166:167]
	v_pk_add_f32 v[216:217], v[216:217], v[168:169]
	v_pk_add_f32 v[202:203], v[202:203], v[170:171]
	v_pk_add_f32 v[204:205], v[204:205], v[172:173]
	v_pk_add_f32 v[206:207], v[206:207], v[174:175]
	v_pk_add_f32 v[208:209], v[208:209], v[176:177]
	v_pk_add_f32 v[210:211], v[210:211], v[178:179]
	v_pk_add_f32 v[212:213], v[212:213], v[180:181]
	v_pk_add_f32 v[214:215], v[214:215], v[182:183]
	v_pk_add_f32 v[216:217], v[216:217], v[184:185]
	v_pk_add_f32 v[202:203], v[202:203], v[186:187]
	v_pk_add_f32 v[204:205], v[204:205], v[188:189]
	v_pk_add_f32 v[206:207], v[206:207], v[190:191]
	v_pk_add_f32 v[208:209], v[208:209], v[192:193]
	v_pk_add_f32 v[210:211], v[210:211], v[194:195]
	v_pk_add_f32 v[212:213], v[212:213], v[196:197]
	v_pk_add_f32 v[214:215], v[214:215], v[198:199]
	v_pk_add_f32 v[216:217], v[216:217], v[200:201]
	v_pk_add_f32 v[202:203], v[202:203], v[18:19]
	v_pk_add_f32 v[204:205], v[204:205], v[20:21]
	v_pk_add_f32 v[206:207], v[206:207], v[22:23]
	v_pk_add_f32 v[208:209], v[208:209], v[24:25]
	v_pk_add_f32 v[210:211], v[210:211], v[26:27]
	v_pk_add_f32 v[212:213], v[212:213], v[28:29]
	v_pk_add_f32 v[214:215], v[214:215], v[30:31]
	v_pk_add_f32 v[216:217], v[216:217], v[32:33]
	v_pk_add_f32 v[202:203], v[202:203], v[66:67]
	v_pk_add_f32 v[204:205], v[204:205], v[68:69]
	v_pk_add_f32 v[206:207], v[206:207], v[70:71]
	v_pk_add_f32 v[208:209], v[208:209], v[72:73]
	v_pk_add_f32 v[210:211], v[210:211], v[74:75]
	v_pk_add_f32 v[212:213], v[212:213], v[76:77]
	v_pk_add_f32 v[214:215], v[214:215], v[78:79]
	v_pk_add_f32 v[216:217], v[216:217], v[80:81]
	v_pk_add_f32 v[202:203], v[202:203], v[82:83]
	v_pk_add_f32 v[204:205], v[204:205], v[84:85]
	v_pk_add_f32 v[206:207], v[206:207], v[86:87]
	v_pk_add_f32 v[208:209], v[208:209], v[88:89]
	v_pk_add_f32 v[210:211], v[210:211], v[90:91]
	v_pk_add_f32 v[212:213], v[212:213], v[92:93]
	v_pk_add_f32 v[214:215], v[214:215], v[94:95]
	v_pk_add_f32 v[216:217], v[216:217], v[96:97]
	v_pk_add_f32 v[66:67], v[202:203], v[204:205]
	v_pk_add_f32 v[68:69], v[206:207], v[208:209]
	v_pk_add_f32 v[70:71], v[210:211], v[212:213]
	v_pk_add_f32 v[72:73], v[214:215], v[216:217]
	v_pk_add_f32 v[66:67], v[66:67], v[68:69]
	v_pk_add_f32 v[70:71], v[70:71], v[72:73]
	v_pk_add_f32 v[66:67], v[66:67], v[70:71]
	v_add_f32_e32 v66, v66, v67
	s_nop 1
	v_add_f32_dpp v66, v66, v66 row_shr:1 row_mask:0xf bank_mask:0xf bound_ctrl:1
	s_nop 1
	v_add_f32_dpp v66, v66, v66 row_shr:2 row_mask:0xf bank_mask:0xf bound_ctrl:1
	s_nop 1
	v_add_f32_dpp v66, v66, v66 row_shr:4 row_mask:0xf bank_mask:0xf bound_ctrl:1
	s_nop 1
	v_add_f32_dpp v66, v66, v66 row_shr:8 row_mask:0xf bank_mask:0xf bound_ctrl:1
	s_nop 0
	v_readlane_b32 s9, v66, 15
	v_readlane_b32 s10, v66, 31
	v_readlane_b32 s11, v66, 47
	v_readlane_b32 vcc_lo, v66, 63
	s_nop 1
	v_mov_b32_e32 v66, s9
	v_add_f32_e32 v66, s10, v66
	v_add_f32_e32 v66, s11, v66
	v_add_f32_e32 v66, vcc_lo, v66
	v_mul_f32_e32 v116, 0x3a800000, v66
	v_mov_b32_e32 v117, v116
	v_pk_add_f32 v[202:203], v[202:203], v[116:117] neg_lo:[0,1] neg_hi:[0,1]
	v_pk_add_f32 v[204:205], v[204:205], v[116:117] neg_lo:[0,1] neg_hi:[0,1]
	v_pk_add_f32 v[206:207], v[206:207], v[116:117] neg_lo:[0,1] neg_hi:[0,1]
	v_pk_add_f32 v[208:209], v[208:209], v[116:117] neg_lo:[0,1] neg_hi:[0,1]
	v_pk_add_f32 v[210:211], v[210:211], v[116:117] neg_lo:[0,1] neg_hi:[0,1]
	v_pk_add_f32 v[212:213], v[212:213], v[116:117] neg_lo:[0,1] neg_hi:[0,1]
	v_pk_add_f32 v[214:215], v[214:215], v[116:117] neg_lo:[0,1] neg_hi:[0,1]
	v_pk_add_f32 v[216:217], v[216:217], v[116:117] neg_lo:[0,1] neg_hi:[0,1]
	v_pk_mul_f32 v[66:67], v[202:203], v[202:203]
	v_pk_mul_f32 v[68:69], v[204:205], v[204:205]
	v_pk_fma_f32 v[66:67], v[206:207], v[206:207], v[66:67]
	v_pk_fma_f32 v[68:69], v[208:209], v[208:209], v[68:69]
	v_pk_fma_f32 v[66:67], v[210:211], v[210:211], v[66:67]
	v_pk_fma_f32 v[68:69], v[212:213], v[212:213], v[68:69]
	v_pk_fma_f32 v[66:67], v[214:215], v[214:215], v[66:67]
	v_pk_fma_f32 v[68:69], v[216:217], v[216:217], v[68:69]
	v_pk_add_f32 v[66:67], v[66:67], v[68:69]
	v_add_f32_e32 v66, v66, v67
	s_nop 1
	v_add_f32_dpp v66, v66, v66 row_shr:1 row_mask:0xf bank_mask:0xf bound_ctrl:1
	s_nop 1
	v_add_f32_dpp v66, v66, v66 row_shr:2 row_mask:0xf bank_mask:0xf bound_ctrl:1
	s_nop 1
	v_add_f32_dpp v66, v66, v66 row_shr:4 row_mask:0xf bank_mask:0xf bound_ctrl:1
	s_nop 1
	v_add_f32_dpp v66, v66, v66 row_shr:8 row_mask:0xf bank_mask:0xf bound_ctrl:1
	s_nop 0
	v_readlane_b32 s9, v66, 15
	v_readlane_b32 s10, v66, 31
; __device__ __forceinline__ void phase_ln(float* R, const float* __restrict__ g, const float* __restrict__ b, bf16_t* xbf, float samp_scale, const float* __restrict__ part, int nsplit, bool f32_all) {
;     ...
;   for (int r = gw; r < MT; r += nw) {
;     float* row = R + (size_t)r * 1024;
;     f32x4 v[4];
; #pragma unroll
;     for (int i = 0; i < 4; ++i) v[i] = *(const f32x4*)(row + i * 256 + lane * 4);
;     if (r >= MP) {
;       for (int sp = 0; sp < nsplit; ++sp) {
;         const float* prow = part + ((size_t)sp * MS + (r - MP)) * 1024;
; #pragma unroll
;         for (int i = 0; i < 4; ++i) v[i] = v[i] + *(const f32x4*)(prow + i * 256 + lane * 4);
;       }
;     }
;     ...
;     const float rstd = rsqrtf(ss * (1.f / 1024.f) + LN_EPS);
; #pragma unroll
;     for (int i = 0; i < 4; ++i) {
;       const f32x4 y = v[i] * rstd * gv[i] + bv[i];
;       if (r >= MP) *(f32x4*)(row + i * 256 + lane * 4) = y * samp_scale;
;       else if (f32_all) *(f32x4*)(row + i * 256 + lane * 4) = y;
;       if (xbf) {
;         u32x2 wv;
;         wv[0] = cvt_pk_bf16(y[0], y[1]); wv[1] = cvt_pk_bf16(y[2], y[3]);
;         *(u32x2*)(xbf + (size_t)r * 1024 + i * 256 + lane * 4) = wv;
;       }
;     }
	v_readlane_b32 s11, v66, 47
	v_readlane_b32 vcc_lo, v66, 63
	s_nop 1
	v_mov_b32_e32 v66, s9
	v_add_f32_e32 v66, s10, v66
	v_add_f32_e32 v66, s11, v66
	v_add_f32_e32 v66, vcc_lo, v66
	v_mul_f32_e32 v66, 0x3a800000, v66
	v_add_f32_e32 v66, 0x3727c5ac, v66
	v_rsq_f32_e32 v118, v66
	s_nop 0
	v_mov_b32_e32 v119, v118
	v_pk_mul_f32 v[202:203], v[202:203], v[118:119]
	v_pk_mul_f32 v[204:205], v[204:205], v[118:119]
	v_pk_mul_f32 v[206:207], v[206:207], v[118:119]
	v_pk_mul_f32 v[208:209], v[208:209], v[118:119]
	v_pk_mul_f32 v[210:211], v[210:211], v[118:119]
	v_pk_mul_f32 v[212:213], v[212:213], v[118:119]
	v_pk_mul_f32 v[214:215], v[214:215], v[118:119]
	v_pk_mul_f32 v[216:217], v[216:217], v[118:119]
	v_pk_fma_f32 v[76:77], v[202:203], v[34:35], v[50:51]
	v_pk_fma_f32 v[78:79], v[204:205], v[36:37], v[52:53]
	v_pk_fma_f32 v[80:81], v[206:207], v[38:39], v[54:55]
	v_pk_fma_f32 v[82:83], v[208:209], v[40:41], v[56:57]
	v_pk_fma_f32 v[84:85], v[210:211], v[42:43], v[58:59]
	v_pk_fma_f32 v[86:87], v[212:213], v[44:45], v[60:61]
	v_pk_fma_f32 v[88:89], v[214:215], v[46:47], v[62:63]
	v_pk_fma_f32 v[90:91], v[216:217], v[48:49], v[64:65]
	s_cmp_lg_u32 s8, 0
	s_cselect_b32 s9, 1.0, 0x3fb504f3
	v_mov_b32_e32 v120, s9
	v_mov_b32_e32 v121, s9
	v_pk_mul_f32 v[202:203], v[76:77], v[120:121]
	v_pk_mul_f32 v[204:205], v[78:79], v[120:121]
	v_pk_mul_f32 v[206:207], v[80:81], v[120:121]
	v_pk_mul_f32 v[208:209], v[82:83], v[120:121]
	v_pk_mul_f32 v[210:211], v[84:85], v[120:121]
	v_pk_mul_f32 v[212:213], v[86:87], v[120:121]
	v_pk_mul_f32 v[214:215], v[88:89], v[120:121]
	v_pk_mul_f32 v[216:217], v[90:91], v[120:121]
	global_store_dwordx4 v114, v[202:205], s[4:5] offset:0
	global_store_dwordx4 v114, v[206:209], s[4:5] offset:1024
	global_store_dwordx4 v114, v[210:213], s[4:5] offset:2048
	global_store_dwordx4 v114, v[214:217], s[4:5] offset:3072
	s_cmp_lg_u32 s8, 0
	s_cbranch_scc1 .Lln2_nosb
	v_cvt_pk_bf16_f32 v92, v76, v77
	v_cvt_pk_bf16_f32 v93, v78, v79
	v_cvt_pk_bf16_f32 v94, v80, v81
	v_cvt_pk_bf16_f32 v95, v82, v83
	v_cvt_pk_bf16_f32 v96, v84, v85
	v_cvt_pk_bf16_f32 v97, v86, v87
	v_cvt_pk_bf16_f32 v98, v88, v89
	v_cvt_pk_bf16_f32 v99, v90, v91
	global_store_dwordx2 v115, v[92:93], s[6:7] offset:0
	global_store_dwordx2 v115, v[94:95], s[6:7] offset:512
	global_store_dwordx2 v115, v[96:97], s[6:7] offset:1024
	global_store_dwordx2 v115, v[98:99], s[6:7] offset:1536
.Lln2_nosb:
	s_add_u32 s0, s0, 0x800000
	s_addc_u32 s1, s1, 0
	global_load_dwordx4 v[18:21], v114, s[0:1] offset:0
	global_load_dwordx4 v[22:25], v114, s[0:1] offset:1024
	global_load_dwordx4 v[26:29], v114, s[0:1] offset:2048
	global_load_dwordx4 v[30:33], v114, s[0:1] offset:3072
	s_waitcnt vmcnt(4)
	v_pk_add_f32 v[66:67], v[0:1], v[2:3]
	v_pk_add_f32 v[68:69], v[4:5], v[6:7]
	v_pk_add_f32 v[70:71], v[8:9], v[10:11]
	v_pk_add_f32 v[72:73], v[12:13], v[14:15]
	v_pk_add_f32 v[66:67], v[66:67], v[68:69]
	v_pk_add_f32 v[70:71], v[70:71], v[72:73]
	v_pk_add_f32 v[66:67], v[66:67], v[70:71]
	v_add_f32_e32 v66, v66, v67
	s_nop 1
	v_add_f32_dpp v66, v66, v66 row_shr:1 row_mask:0xf bank_mask:0xf bound_ctrl:1
	s_nop 1
	v_add_f32_dpp v66, v66, v66 row_shr:2 row_mask:0xf bank_mask:0xf bound_ctrl:1
	s_nop 1
	v_add_f32_dpp v66, v66, v66 row_shr:4 row_mask:0xf bank_mask:0xf bound_ctrl:1
	s_nop 1
	v_add_f32_dpp v66, v66, v66 row_shr:8 row_mask:0xf bank_mask:0xf bound_ctrl:1
	s_nop 0
	v_readlane_b32 s9, v66, 15
	v_readlane_b32 s10, v66, 31
	v_readlane_b32 s11, v66, 47
	v_readlane_b32 vcc_lo, v66, 63
	s_nop 1
	v_mov_b32_e32 v66, s9
	v_add_f32_e32 v66, s10, v66
	v_add_f32_e32 v66, s11, v66
	v_add_f32_e32 v66, vcc_lo, v66
	v_mul_f32_e32 v116, 0x3a800000, v66
	v_mov_b32_e32 v117, v116
	v_pk_add_f32 v[0:1], v[0:1], v[116:117] neg_lo:[0,1] neg_hi:[0,1]
	v_pk_add_f32 v[2:3], v[2:3], v[116:117] neg_lo:[0,1] neg_hi:[0,1]
	v_pk_add_f32 v[4:5], v[4:5], v[116:117] neg_lo:[0,1] neg_hi:[0,1]
	v_pk_add_f32 v[6:7], v[6:7], v[116:117] neg_lo:[0,1] neg_hi:[0,1]
	v_pk_add_f32 v[8:9], v[8:9], v[116:117] neg_lo:[0,1] neg_hi:[0,1]
	v_pk_add_f32 v[10:11], v[10:11], v[116:117] neg_lo:[0,1] neg_hi:[0,1]
	v_pk_add_f32 v[12:13], v[12:13], v[116:117] neg_lo:[0,1] neg_hi:[0,1]
	v_pk_add_f32 v[14:15], v[14:15], v[116:117] neg_lo:[0,1] neg_hi:[0,1]
	v_pk_mul_f32 v[66:67], v[0:1], v[0:1]
	v_pk_mul_f32 v[68:69], v[2:3], v[2:3]
	v_pk_fma_f32 v[66:67], v[4:5], v[4:5], v[66:67]
	v_pk_fma_f32 v[68:69], v[6:7], v[6:7], v[68:69]
	v_pk_fma_f32 v[66:67], v[8:9], v[8:9], v[66:67]
	v_pk_fma_f32 v[68:69], v[10:11], v[10:11], v[68:69]
	v_pk_fma_f32 v[66:67], v[12:13], v[12:13], v[66:67]
	v_pk_fma_f32 v[68:69], v[14:15], v[14:15], v[68:69]
	v_pk_add_f32 v[66:67], v[66:67], v[68:69]
	v_add_f32_e32 v66, v66, v67
	s_nop 1
	v_add_f32_dpp v66, v66, v66 row_shr:1 row_mask:0xf bank_mask:0xf bound_ctrl:1
	s_nop 1
	v_add_f32_dpp v66, v66, v66 row_shr:2 row_mask:0xf bank_mask:0xf bound_ctrl:1
	s_nop 1
	v_add_f32_dpp v66, v66, v66 row_shr:4 row_mask:0xf bank_mask:0xf bound_ctrl:1
	s_nop 1
	v_add_f32_dpp v66, v66, v66 row_shr:8 row_mask:0xf bank_mask:0xf bound_ctrl:1
	s_nop 0
	v_readlane_b32 s9, v66, 15
	v_readlane_b32 s10, v66, 31
	v_readlane_b32 s11, v66, 47
	v_readlane_b32 vcc_lo, v66, 63
	s_nop 1
	v_mov_b32_e32 v66, s9
	v_add_f32_e32 v66, s10, v66
	v_add_f32_e32 v66, s11, v66
	v_add_f32_e32 v66, vcc_lo, v66
	v_mul_f32_e32 v66, 0x3a800000, v66
	v_add_f32_e32 v66, 0x3727c5ac, v66
	v_rsq_f32_e32 v118, v66
	s_nop 0
	v_mov_b32_e32 v119, v118
	v_pk_mul_f32 v[0:1], v[0:1], v[118:119]
	v_pk_mul_f32 v[2:3], v[2:3], v[118:119]
	v_pk_mul_f32 v[4:5], v[4:5], v[118:119]
	v_pk_mul_f32 v[6:7], v[6:7], v[118:119]
	v_pk_mul_f32 v[8:9], v[8:9], v[118:119]
	v_pk_mul_f32 v[10:11], v[10:11], v[118:119]
	v_pk_mul_f32 v[12:13], v[12:13], v[118:119]
	v_pk_mul_f32 v[14:15], v[14:15], v[118:119]
	v_pk_fma_f32 v[76:77], v[0:1], v[34:35], v[50:51]
	v_pk_fma_f32 v[78:79], v[2:3], v[36:37], v[52:53]
	v_pk_fma_f32 v[80:81], v[4:5], v[38:39], v[54:55]
	v_pk_fma_f32 v[82:83], v[6:7], v[40:41], v[56:57]
	v_pk_fma_f32 v[84:85], v[8:9], v[42:43], v[58:59]
	v_pk_fma_f32 v[86:87], v[10:11], v[44:45], v[60:61]
	v_pk_fma_f32 v[88:89], v[12:13], v[46:47], v[62:63]
	v_pk_fma_f32 v[90:91], v[14:15], v[48:49], v[64:65]
	s_cmp_lg_u32 s8, 0
	s_cbranch_scc1 .Lln2_f32_0
	v_cvt_pk_bf16_f32 v92, v76, v77
	v_cvt_pk_bf16_f32 v93, v78, v79
	v_cvt_pk_bf16_f32 v94, v80, v81
	v_cvt_pk_bf16_f32 v95, v82, v83
	v_cvt_pk_bf16_f32 v96, v84, v85
	v_cvt_pk_bf16_f32 v97, v86, v87
	v_cvt_pk_bf16_f32 v98, v88, v89
	v_cvt_pk_bf16_f32 v99, v90, v91
	global_store_dwordx2 v115, v[92:93], s[2:3] offset:0
	global_store_dwordx2 v115, v[94:95], s[2:3] offset:512
	global_store_dwordx2 v115, v[96:97], s[2:3] offset:1024
	global_store_dwordx2 v115, v[98:99], s[2:3] offset:1536
	s_branch .Lln2_st_0

; __device__ __forceinline__ void phase_ln(float* R, const float* __restrict__ g, const float* __restrict__ b, bf16_t* xbf, float samp_scale, const float* __restrict__ part, int nsplit, bool f32_all) {
;     ...
;   for (int r = gw; r < MT; r += nw) {
;     float* row = R + (size_t)r * 1024;
;     f32x4 v[4];
; #pragma unroll
;     for (int i = 0; i < 4; ++i) v[i] = *(const f32x4*)(row + i * 256 + lane * 4);
;     if (r >= MP) {
;       for (int sp = 0; sp < nsplit; ++sp) {
;         const float* prow = part + ((size_t)sp * MS + (r - MP)) * 1024;
; #pragma unroll
;         for (int i = 0; i < 4; ++i) v[i] = v[i] + *(const f32x4*)(prow + i * 256 + lane * 4);
;       }
;     }
;     float s = 0.f;
; #pragma unroll
;     for (int i = 0; i < 4; ++i) s += v[i][0] + v[i][1] + v[i][2] + v[i][3];
; #pragma unroll
;     for (int o = 32; o >= 1; o >>= 1) s += __shfl_xor(s, o);
;     const float mean = s * (1.f / 1024.f);
;     float ss = 0.f;
; #pragma unroll
;     for (int i = 0; i < 4; ++i) { v[i] = v[i] - mean; ss += v[i][0] * v[i][0] + v[i][1] * v[i][1] + v[i][2] * v[i][2] + v[i][3] * v[i][3]; }
; #pragma unroll
;     for (int o = 32; o >= 1; o >>= 1) ss += __shfl_xor(ss, o);
;     const float rstd = rsqrtf(ss * (1.f / 1024.f) + LN_EPS);
; #pragma unroll
;     for (int i = 0; i < 4; ++i) {
;       const f32x4 y = v[i] * rstd * gv[i] + bv[i];
;       if (r >= MP) *(f32x4*)(row + i * 256 + lane * 4) = y * samp_scale;
;       else if (f32_all) *(f32x4*)(row + i * 256 + lane * 4) = y;
;       if (xbf) {
;         u32x2 wv;
;         wv[0] = cvt_pk_bf16(y[0], y[1]); wv[1] = cvt_pk_bf16(y[2], y[3]);
;         *(u32x2*)(xbf + (size_t)r * 1024 + i * 256 + lane * 4) = wv;
;       }
;     }
;   }
.Lln2_st_15:
	s_add_u32 s2, s2, 0x400000
	s_addc_u32 s3, s3, 0
	s_branch .Lln2_end
